# GEMM K-loop: per-phase s_setprio flips removed, one static priority raise for waves 4-7 before the tile loop (reset at the phase barrier)
# speedup vs baseline: 1.0103x; 1.0103x over previous
; #define PG8_STAGE(bufoff, gbase, voff) do { _Pragma("unroll") for (int _i = 0; _i < 2; ++_i) \
;         __builtin_amdgcn_global_load_lds((const unsigned*)((const char*)(gbase) + (voff)[_i]), (LAS unsigned*)(lds + (bufoff) + ldsw + _i * 8192), 16, 0, 0); } while (0)
; #define PG8_WAIT_V(n) asm volatile("s_waitcnt vmcnt(" #n ")" ::: "memory")
; #define PG8_BAR __builtin_amdgcn_s_barrier()
; template <class F>
; DI void gemm_phase(const int tid, LAS unsigned char* lds, const bf16_t* Ap, int lda, const bf16_t* Bp, int ldb, int M, int N, int K, int G, int c, bool direct, const F& E) {
;     const int wid = __builtin_amdgcn_readfirstlane(tid >> 6), lane = tid & 63, wr = wid >> 2, wc = wid & 3, fr = lane & 15, fq = lane >> 4;
;     const int nt = K / BK;
;     Order S; S.init(M, N, G, c, direct);
;     unsigned voffA[2], voffB[2];
; #pragma unroll
;     for (int i = 0; i < 2; ++i) { int R, C; stage_rc(tid * 16 + i * 8192, R, C); const int Rb = (R & ~31) + perm32(R & 31);
;         voffA[i] = (unsigned)(R * lda + C) * 2u; voffB[i] = (unsigned)(Rb * ldb + C) * 2u; }
;     const size_t kstep = (size_t)(BK * 2);
;     const size_t hsA = (size_t)HALF * lda * 2, hsB = (size_t)HALF * ldb * 2;
;     const size_t tsA = 2 * hsA, tsB = 2 * hsB;
;     const unsigned ldsw = (unsigned)wid * 1024u;
;     const int aoff = lds_byte(wr * 64 + fr, fq * 8), boff = lds_byte(wc * 32 + fr, fq * 8);
;     ...
;     const char* cA = (const char*)Ap + (size_t)cur.pm * tsA; const char* cB = (const char*)Bp + (size_t)cur.pn * tsB;
;     PG8_STAGE(PG8_SB(0, 0), cB, voffB); PG8_STAGE(PG8_SA(0, 0), cA, voffA); PG8_STAGE(PG8_SB(0, 1), cB + hsB, voffB); PG8_STAGE(PG8_SA(0, 1), cA + hsA, voffA);
;     if (wr == 1) PG8_BAR;
;     PG8_WAIT_V(4); PG8_BAR;
;     PG8_STAGE(PG8_SB(1, 0), cB + kstep, voffB); PG8_STAGE(PG8_SA(1, 0), cA + kstep, voffA); PG8_STAGE(PG8_SB(1, 1), cB + hsB + kstep, voffB);
;     PG8_WAIT_V(6); PG8_BAR;
.LBB0_648:
	s_add_i32 m0, s28, 0x18000
	v_lshl_add_u64 v[0:1], v[0:1], 0, s[30:31]
	s_waitcnt vmcnt(4)
	s_barrier
	global_load_lds_dwordx4 v[0:1], off
	v_lshl_add_u64 v[0:1], v[2:3], 0, s[30:31]
	s_add_i32 m0, s28, 0x1a000
	s_add_i32 s62, s28, 0x8000
	global_load_lds_dwordx4 v[0:1], off
	v_lshl_add_u64 v[0:1], v[4:5], 0, s[30:31]
	s_mov_b32 m0, s62
	s_add_i32 s63, s28, 0xa000
	global_load_lds_dwordx4 v[0:1], off
	v_lshl_add_u64 v[0:1], v[6:7], 0, s[30:31]
	s_mov_b32 m0, s63
	v_lshrrev_b32_e32 v18, 1, v182
	global_load_lds_dwordx4 v[0:1], off
	s_add_i32 m0, s28, 0x1c000
	v_lshl_add_u64 v[0:1], v[8:9], 0, s[30:31]
	global_load_lds_dwordx4 v[0:1], off
	v_lshl_add_u64 v[0:1], v[10:11], 0, s[30:31]
	s_add_i32 m0, s28, 0x1e000
	v_and_b32_e32 v18, 24, v18
	global_load_lds_dwordx4 v[0:1], off
	v_and_b32_e32 v188, 15, v182
	v_lshlrev_b32_e32 v19, 1, v18
	v_lshlrev_b32_e32 v20, 2, v182
	s_lshl_b32 s5, s0, 6
	v_lshl_or_b32 v19, v188, 6, v19
	s_lshl_b32 s0, s0, 13
	v_and_b32_e32 v20, 32, v20
	s_lshl_b32 s1, s1, 5
	s_lshr_b32 s26, s19, 6
	v_bitop3_b32 v21, v19, s0, v20 bitop3:0xde
	s_and_b32 s0, s1, 0x60
	v_writelane_b32 v255, s5, 16
	s_bfe_u32 s1, s1, 0x10006
	s_xor_b64 s[86:87], s[38:39], -1
	s_lshl_b32 s4, s0, 7
	s_ashr_i32 s64, s17, 31
	s_ashr_i32 s65, s16, 31
	s_lshr_b32 s84, s18, 3
	s_lshl_b32 s66, s40, 3
	s_add_i32 s67, s26, -2
	v_writelane_b32 v255, s1, 18
	s_or_b32 s1, s0, 0x80
	v_bitop3_b32 v189, s4, v19, v20 bitop3:0xf6
	v_mov_b32_e32 v0, 0x4f
	s_add_u32 s4, s22, 0x5800
	v_or_b32_e32 v183, s5, v188
	v_bitop3_b32 v192, s5, v0, v188 bitop3:0xc8
	s_addc_u32 s5, s23, 0
	v_writelane_b32 v254, s4, 54
	v_cvt_f32_u32_e32 v0, s66
	v_or_b32_e32 v194, s0, v18
	v_writelane_b32 v254, s5, 55
	s_add_u32 s4, s22, 0xb000
	s_addc_u32 s5, s23, 0
	v_writelane_b32 v254, s4, 56
	v_rcp_iflag_f32_e32 v0, v0
	v_bitop3_b32 v196, s0, 56, v18 bitop3:0xc8
	v_writelane_b32 v254, s5, 57
	s_add_u32 s4, s22, 0x2c00
	s_addc_u32 s5, s23, 0
	v_writelane_b32 v255, s4, 4
	v_mul_f32_e32 v0, 0x4f7ffffe, v0
	v_cvt_u32_f32_e32 v0, v0
	v_writelane_b32 v255, s5, 5
	s_add_u32 s4, s22, 0x8400
	s_addc_u32 s5, s23, 0
	v_writelane_b32 v255, s4, 6
	v_or_b32_e32 v193, s1, v18
	v_bitop3_b32 v200, s1, 56, v18 bitop3:0xc8
	v_writelane_b32 v255, s5, 7
	s_add_u32 s4, s22, 0xdc00
	s_addc_u32 s5, s23, 0
	v_writelane_b32 v255, s4, 8
	s_waitcnt vmcnt(6)
	s_mov_b32 s19, s37
	v_cmp_lt_u32_e64 s[38:39], 1, v188
	v_writelane_b32 v255, s5, 9
	v_readlane_b32 s4, v254, 49
	v_readlane_b32 s5, v254, 50
	s_add_u32 s72, s4, 0x2c00
	s_addc_u32 s73, s5, 0
	s_lshr_b32 s0, s1, 6
	v_writelane_b32 v255, s0, 20
	s_sub_i32 s0, 0, s66
	v_readfirstlane_b32 s1, v0
	s_mul_i32 s0, s0, s1
	v_add_u32_e32 v0, v14, v12
	v_writelane_b32 v255, s86, 14
	s_mul_hi_u32 s0, s1, s0
	v_add_lshl_u32 v180, v0, v13, 1
	v_add_u32_e32 v0, v17, v15
	v_writelane_b32 v255, s87, 15
	s_add_i32 s85, s1, s0
	v_lshl_add_u64 v[204:205], s[24:25], 0, v[180:181]
	v_add_lshl_u32 v180, v0, v16, 1
	v_writelane_b32 v255, s84, 10
	v_cmp_gt_u32_e64 s[40:41], 2, v188
	v_cmp_lt_u32_e64 s[42:43], 13, v188
	v_add_u32_e32 v190, -12, v188
	v_mov_b32_e32 v191, v181
	v_lshlrev_b32_e32 v198, 11, v196
	s_mov_b32 s68, 0
	v_mov_b32_e32 v195, v181
	v_lshl_add_u64 v[206:207], s[24:25], 0, v[180:181]
	v_add_u32_e32 v197, 0, v21
	v_writelane_b32 v255, s85, 12
	v_readlane_b32 s98, v255, 22
	s_lshr_b32 s98, s98, 8
	s_cmp_eq_u32 s98, 1
	s_cbranch_scc0 .Lgprio_done
	s_setprio 1
.Lgprio_done:
	s_barrier
	s_branch .LBB0_650

; #define PG8_STAGE(bufoff, gbase, voff) do { _Pragma("unroll") for (int _i = 0; _i < 2; ++_i) \
;         __builtin_amdgcn_global_load_lds((const unsigned*)((const char*)(gbase) + (voff)[_i]), (LAS unsigned*)(lds + (bufoff) + ldsw + _i * 8192), 16, 0, 0); } while (0)
; #define PG8_LDA(dst, b, h) do { _Pragma("unroll") for (int m = 0; m < 4; ++m) _Pragma("unroll") for (int k = 0; k < 2; ++k) dst[m][k] = *(const LAS bf16x8*)(lds + PG8_SA(b, h) + aoff + m * 2048 + k * 1024); } while (0)
; #define PG8_LDB(dst, b, h) do { _Pragma("unroll") for (int n = 0; n < 2; ++n) _Pragma("unroll") for (int k = 0; k < 2; ++k) dst[n][k] = *(const LAS bf16x8*)(lds + PG8_SB(b, h) + boff + n * 2048 + k * 1024); } while (0)
; #define PG8_MMA(ai, bj, At, Bt) do { __builtin_amdgcn_s_setprio(1); _Pragma("unroll") for (int m = 0; m < 4; ++m) _Pragma("unroll") for (int n = 0; n < 2; ++n) _Pragma("unroll") for (int k = 0; k < 2; ++k) \
;         acc[ai][bj][m][n] = __builtin_amdgcn_mfma_f32_16x16x32_bf16(Bt[n][k], At[m][k], acc[ai][bj][m][n], 0, 0, 0); __builtin_amdgcn_s_setprio(0); } while (0)
; #define PG8_WAIT_V(n) asm volatile("s_waitcnt vmcnt(" #n ")" ::: "memory")
; #define PG8_BAR __builtin_amdgcn_s_barrier()
; template <class F>
; DI void gemm_phase(const int tid, LAS unsigned char* lds, const bf16_t* Ap, int lda, const bf16_t* Bp, int ldb, int M, int N, int K, int G, int c, bool direct, const F& E) {
;     ...
;         for (int t = 0; t < nt; t += 2) {
;             const bool last = (t == nt - 2);
;             const char* a1 = cA + (size_t)(t + 1) * kstep;
;             const char* a2 = last ? nA : cA + (size_t)(t + 2) * kstep; const char* b2 = last ? nB : cB + (size_t)(t + 2) * kstep;
;             const char* a3 = a2 + kstep; const char* b3 = b2 + kstep;
;             PG8_LDB(B0, 0, 0); PG8_SCHED; PG8_LDA(At, 0, 0); PG8_STAGE(PG8_SA(1, 1), a1 + hsA, voffA);
;             PG8_WAIT_L(8); PG8_BAR; PG8_WAIT_L(0); PG8_MMA(0, 0, At, B0); PG8_BAR; PG8_SCHED;
;             PG8_LDB(B1, 0, 1); PG8_STAGE(PG8_SB(0, 0), b2, voffB);
;             PG8_BAR; PG8_WAIT_L(0); PG8_MMA(0, 1, At, B1); PG8_BAR;
;             PG8_LDA(At, 0, 1); PG8_STAGE(PG8_SA(0, 0), a2, voffA);
;             PG8_BAR; PG8_WAIT_L(0); PG8_MMA(1, 0, At, B0); PG8_BAR; PG8_SCHED;
;             PG8_STAGE(PG8_SB(0, 1), b2 + hsB, voffB);
;             PG8_WAIT_V(6); PG8_BAR; PG8_MMA(1, 1, At, B1); PG8_BAR;
.LBB0_657:
	s_add_i32 s81, s76, 2
	s_add_u32 s78, s74, 0x80
	s_addc_u32 s77, s75, 0
	s_add_i32 s82, 0, 0x10000
	v_add_u32_e32 v140, s82, v189
	ds_read_b128 v[128:131], v140
	ds_read_b128 v[132:135], v140 offset:1024
	ds_read_b128 v[136:139], v140 offset:2048
	ds_read_b128 v[140:143], v140 offset:3072
	s_cmp_eq_u32 s67, s76
	s_cselect_b32 s76, s0, s78
	s_cselect_b32 s77, s1, s77
	s_cselect_b32 s79, s5, s80
	s_cselect_b32 s78, s4, s71
	v_lshl_add_u64 v[208:209], s[74:75], 0, v[204:205]
	s_add_i32 m0, s28, 0xc000
	ds_read_b128 v[144:147], v197
	ds_read_b128 v[148:151], v197 offset:1024
	ds_read_b128 v[152:155], v197 offset:2048
	ds_read_b128 v[156:159], v197 offset:3072
	ds_read_b128 v[160:163], v197 offset:4096
	ds_read_b128 v[164:167], v197 offset:5120
	ds_read_b128 v[168:171], v197 offset:6144
	ds_read_b128 v[172:175], v197 offset:7168
	global_load_lds_dwordx4 v[208:209], off
	v_lshl_add_u64 v[208:209], s[74:75], 0, v[206:207]
	s_add_i32 m0, s28, 0xe000
	s_nop 0
	global_load_lds_dwordx4 v[208:209], off
	s_waitcnt lgkmcnt(8)
	s_barrier
	s_waitcnt lgkmcnt(0)
	s_waitcnt lgkmcnt(0)
	v_mfma_f32_16x16x32_bf16 v[124:127], v[128:131], v[144:147], v[124:127]
	v_mfma_f32_16x16x32_bf16 v[120:123], v[136:139], v[144:147], v[120:123]
	v_mfma_f32_16x16x32_bf16 v[116:119], v[128:131], v[152:155], v[116:119]
	v_mfma_f32_16x16x32_bf16 v[104:107], v[136:139], v[152:155], v[104:107]
	v_mfma_f32_16x16x32_bf16 v[100:103], v[128:131], v[160:163], v[100:103]
	v_mfma_f32_16x16x32_bf16 v[88:91], v[136:139], v[160:163], v[88:91]
	v_mfma_f32_16x16x32_bf16 v[84:87], v[128:131], v[168:171], v[84:87]
	v_mfma_f32_16x16x32_bf16 v[72:75], v[136:139], v[168:171], v[72:75]
	v_mfma_f32_16x16x32_bf16 v[124:127], v[132:135], v[148:151], v[124:127]
	v_mfma_f32_16x16x32_bf16 v[120:123], v[140:143], v[148:151], v[120:123]
	v_mfma_f32_16x16x32_bf16 v[116:119], v[132:135], v[156:159], v[116:119]
	v_mfma_f32_16x16x32_bf16 v[104:107], v[140:143], v[156:159], v[104:107]
	v_mfma_f32_16x16x32_bf16 v[100:103], v[132:135], v[164:167], v[100:103]
	v_mfma_f32_16x16x32_bf16 v[88:91], v[140:143], v[164:167], v[88:91]
	v_mfma_f32_16x16x32_bf16 v[84:87], v[132:135], v[172:175], v[84:87]
	v_mfma_f32_16x16x32_bf16 v[72:75], v[140:143], v[172:175], v[72:75]
	s_barrier
	s_add_i32 s82, s82, s27
	v_add_u32_e32 v180, s95, v189
	v_lshl_add_u64 v[224:225], s[78:79], 0, v[178:179]
	s_mov_b32 m0, s82
	ds_read_b128 v[208:211], v180
	ds_read_b128 v[212:215], v180 offset:1024
	ds_read_b128 v[216:219], v180 offset:2048
	ds_read_b128 v[220:223], v180 offset:3072
	global_load_lds_dwordx4 v[224:225], off
	v_lshl_add_u64 v[226:227], s[78:79], 0, v[186:187]
	s_add_i32 m0, s82, 0x2000
	s_nop 0
	global_load_lds_dwordx4 v[226:227], off
	s_barrier
	s_waitcnt lgkmcnt(0)
	s_waitcnt lgkmcnt(0)
	v_mfma_f32_16x16x32_bf16 v[112:115], v[208:211], v[144:147], v[112:115]
	v_mfma_f32_16x16x32_bf16 v[108:111], v[216:219], v[144:147], v[108:111]
	v_mfma_f32_16x16x32_bf16 v[96:99], v[208:211], v[152:155], v[96:99]
	v_mfma_f32_16x16x32_bf16 v[92:95], v[216:219], v[152:155], v[92:95]
	v_mfma_f32_16x16x32_bf16 v[80:83], v[208:211], v[160:163], v[80:83]
	v_mfma_f32_16x16x32_bf16 v[76:79], v[216:219], v[160:163], v[76:79]
	v_mfma_f32_16x16x32_bf16 v[68:71], v[208:211], v[168:171], v[68:71]
	v_mfma_f32_16x16x32_bf16 v[64:67], v[216:219], v[168:171], v[64:67]
	v_mfma_f32_16x16x32_bf16 v[112:115], v[212:215], v[148:151], v[112:115]
	v_mfma_f32_16x16x32_bf16 v[108:111], v[220:223], v[148:151], v[108:111]
	v_mfma_f32_16x16x32_bf16 v[96:99], v[212:215], v[156:159], v[96:99]
	v_mfma_f32_16x16x32_bf16 v[92:95], v[220:223], v[156:159], v[92:95]
	v_mfma_f32_16x16x32_bf16 v[80:83], v[212:215], v[164:167], v[80:83]
	v_mfma_f32_16x16x32_bf16 v[76:79], v[220:223], v[164:167], v[76:79]
	v_mfma_f32_16x16x32_bf16 v[68:71], v[212:215], v[172:175], v[68:71]
	v_mfma_f32_16x16x32_bf16 v[64:67], v[220:223], v[172:175], v[64:67]
	s_mov_b32 m0, s28
	v_lshl_add_u64 v[228:229], s[76:77], 0, v[176:177]
	s_barrier
	ds_read_b128 v[144:147], v197 offset:16384
	ds_read_b128 v[148:151], v197 offset:17408
	ds_read_b128 v[152:155], v197 offset:18432
	ds_read_b128 v[156:159], v197 offset:19456
	ds_read_b128 v[160:163], v197 offset:20480
	ds_read_b128 v[164:167], v197 offset:21504
	ds_read_b128 v[168:171], v197 offset:22528
	ds_read_b128 v[172:175], v197 offset:23552
	global_load_lds_dwordx4 v[228:229], off
	v_lshl_add_u64 v[242:243], s[76:77], 0, v[184:185]
	s_mov_b32 m0, s34
	s_nop 0
	global_load_lds_dwordx4 v[242:243], off
	s_barrier
	s_waitcnt lgkmcnt(0)
	s_waitcnt lgkmcnt(0)
	v_mfma_f32_16x16x32_bf16 v[60:63], v[128:131], v[144:147], v[60:63]
	v_mfma_f32_16x16x32_bf16 v[56:59], v[136:139], v[144:147], v[56:59]
	v_mfma_f32_16x16x32_bf16 v[52:55], v[128:131], v[152:155], v[52:55]
	v_mfma_f32_16x16x32_bf16 v[40:43], v[136:139], v[152:155], v[40:43]
	v_mfma_f32_16x16x32_bf16 v[36:39], v[128:131], v[160:163], v[36:39]
	v_mfma_f32_16x16x32_bf16 v[16:19], v[136:139], v[160:163], v[16:19]
	v_mfma_f32_16x16x32_bf16 v[12:15], v[128:131], v[168:171], v[12:15]
	v_mfma_f32_16x16x32_bf16 v[0:3], v[136:139], v[168:171], v[0:3]
	v_mfma_f32_16x16x32_bf16 v[60:63], v[132:135], v[148:151], v[60:63]
	v_mfma_f32_16x16x32_bf16 v[56:59], v[140:143], v[148:151], v[56:59]
	v_mfma_f32_16x16x32_bf16 v[52:55], v[132:135], v[156:159], v[52:55]
	v_mfma_f32_16x16x32_bf16 v[40:43], v[140:143], v[156:159], v[40:43]
	v_mfma_f32_16x16x32_bf16 v[36:39], v[132:135], v[164:167], v[36:39]
	v_mfma_f32_16x16x32_bf16 v[16:19], v[140:143], v[164:167], v[16:19]
	v_mfma_f32_16x16x32_bf16 v[12:15], v[132:135], v[172:175], v[12:15]
	v_mfma_f32_16x16x32_bf16 v[0:3], v[140:143], v[172:175], v[0:3]
	s_barrier
; #define PG8_STAGE(bufoff, gbase, voff) do { _Pragma("unroll") for (int _i = 0; _i < 2; ++_i) \
;         __builtin_amdgcn_global_load_lds((const unsigned*)((const char*)(gbase) + (voff)[_i]), (LAS unsigned*)(lds + (bufoff) + ldsw + _i * 8192), 16, 0, 0); } while (0)
; #define PG8_LDA(dst, b, h) do { _Pragma("unroll") for (int m = 0; m < 4; ++m) _Pragma("unroll") for (int k = 0; k < 2; ++k) dst[m][k] = *(const LAS bf16x8*)(lds + PG8_SA(b, h) + aoff + m * 2048 + k * 1024); } while (0)
; #define PG8_LDB(dst, b, h) do { _Pragma("unroll") for (int n = 0; n < 2; ++n) _Pragma("unroll") for (int k = 0; k < 2; ++k) dst[n][k] = *(const LAS bf16x8*)(lds + PG8_SB(b, h) + boff + n * 2048 + k * 1024); } while (0)
; #define PG8_MMA(ai, bj, At, Bt) do { __builtin_amdgcn_s_setprio(1); _Pragma("unroll") for (int m = 0; m < 4; ++m) _Pragma("unroll") for (int n = 0; n < 2; ++n) _Pragma("unroll") for (int k = 0; k < 2; ++k) \
;         acc[ai][bj][m][n] = __builtin_amdgcn_mfma_f32_16x16x32_bf16(Bt[n][k], At[m][k], acc[ai][bj][m][n], 0, 0, 0); __builtin_amdgcn_s_setprio(0); } while (0)
; #define PG8_WAIT_V(n) asm volatile("s_waitcnt vmcnt(" #n ")" ::: "memory")
; #define PG8_WAIT_L(n) asm volatile("s_waitcnt lgkmcnt(" #n ")" ::: "memory")
; #define PG8_BAR __builtin_amdgcn_s_barrier()
; #define PG8_SCHED __builtin_amdgcn_sched_barrier(0)
; template <class F>
; DI void gemm_phase(const int tid, LAS unsigned char* lds, const bf16_t* Ap, int lda, const bf16_t* Bp, int ldb, int M, int N, int K, int G, int c, bool direct, const F& E) {
;     ...
;             PG8_STAGE(PG8_SB(0, 1), b2 + hsB, voffB);
;             PG8_WAIT_V(6); PG8_BAR; PG8_MMA(1, 1, At, B1); PG8_BAR;
;             PG8_LDB(B0, 1, 0); PG8_SCHED; PG8_LDA(At, 1, 0); PG8_STAGE(PG8_SA(0, 1), a2 + hsA, voffA);
;             PG8_WAIT_L(8); PG8_BAR; PG8_WAIT_L(0); PG8_MMA(0, 0, At, B0); PG8_BAR; PG8_SCHED;
;             PG8_LDB(B1, 1, 1); PG8_STAGE(PG8_SB(1, 0), b3, voffB);
;             PG8_BAR; PG8_WAIT_L(0); PG8_MMA(0, 1, At, B1); PG8_BAR;
;             PG8_LDA(At, 1, 1); PG8_STAGE(PG8_SA(1, 0), a3, voffA);
;             PG8_BAR; PG8_WAIT_L(0); PG8_MMA(1, 0, At, B0); PG8_BAR; PG8_SCHED;
	s_add_u32 s78, s78, s46
	s_addc_u32 s79, s79, 0
	s_add_i32 s82, s95, s27
	v_lshl_add_u64 v[244:245], s[78:79], 0, v[178:179]
	s_mov_b32 m0, s82
	v_lshl_add_u64 v[246:247], s[78:79], 0, v[186:187]
	global_load_lds_dwordx4 v[244:245], off
	s_add_i32 m0, s82, 0x2000
	s_nop 0
	global_load_lds_dwordx4 v[246:247], off
	s_waitcnt vmcnt(6)
	s_barrier
	v_mfma_f32_16x16x32_bf16 v[48:51], v[208:211], v[144:147], v[48:51]
	v_mfma_f32_16x16x32_bf16 v[44:47], v[216:219], v[144:147], v[44:47]
	v_mfma_f32_16x16x32_bf16 v[24:27], v[208:211], v[152:155], v[24:27]
	v_mfma_f32_16x16x32_bf16 v[20:23], v[216:219], v[152:155], v[20:23]
	v_mfma_f32_16x16x32_bf16 v[28:31], v[208:211], v[160:163], v[28:31]
	v_mfma_f32_16x16x32_bf16 v[32:35], v[216:219], v[160:163], v[32:35]
	v_mfma_f32_16x16x32_bf16 v[8:11], v[208:211], v[168:171], v[8:11]
	v_mfma_f32_16x16x32_bf16 v[4:7], v[216:219], v[168:171], v[4:7]
	v_mfma_f32_16x16x32_bf16 v[48:51], v[212:215], v[148:151], v[48:51]
	v_mfma_f32_16x16x32_bf16 v[44:47], v[220:223], v[148:151], v[44:47]
	v_mfma_f32_16x16x32_bf16 v[24:27], v[212:215], v[156:159], v[24:27]
	v_mfma_f32_16x16x32_bf16 v[20:23], v[220:223], v[156:159], v[20:23]
	v_mfma_f32_16x16x32_bf16 v[28:31], v[212:215], v[164:167], v[28:31]
	v_mfma_f32_16x16x32_bf16 v[32:35], v[220:223], v[164:167], v[32:35]
	v_mfma_f32_16x16x32_bf16 v[8:11], v[212:215], v[172:175], v[8:11]
	v_mfma_f32_16x16x32_bf16 v[4:7], v[220:223], v[172:175], v[4:7]
	s_add_i32 s78, 0, 0x18000
	v_add_u32_e32 v140, s78, v189
	s_barrier
	ds_read_b128 v[128:131], v140
	ds_read_b128 v[132:135], v140 offset:1024
	ds_read_b128 v[136:139], v140 offset:2048
	ds_read_b128 v[140:143], v140 offset:3072
	s_add_u32 s76, s76, s24
	s_addc_u32 s77, s77, 0
	s_mov_b32 m0, s60
	v_lshl_add_u64 v[208:209], s[76:77], 0, v[176:177]
	ds_read_b128 v[144:147], v197 offset:32768
	ds_read_b128 v[148:151], v197 offset:33792
	ds_read_b128 v[152:155], v197 offset:34816
	ds_read_b128 v[156:159], v197 offset:35840
	ds_read_b128 v[160:163], v197 offset:36864
	ds_read_b128 v[164:167], v197 offset:37888
	ds_read_b128 v[168:171], v197 offset:38912
	ds_read_b128 v[172:175], v197 offset:39936
	global_load_lds_dwordx4 v[208:209], off
	v_lshl_add_u64 v[208:209], s[76:77], 0, v[184:185]
	s_mov_b32 m0, s61
	s_nop 0
	global_load_lds_dwordx4 v[208:209], off
	s_waitcnt lgkmcnt(8)
	s_barrier
	s_waitcnt lgkmcnt(0)
	s_waitcnt lgkmcnt(0)
	v_mfma_f32_16x16x32_bf16 v[124:127], v[128:131], v[144:147], v[124:127]
	v_mfma_f32_16x16x32_bf16 v[120:123], v[136:139], v[144:147], v[120:123]
	v_mfma_f32_16x16x32_bf16 v[116:119], v[128:131], v[152:155], v[116:119]
	v_mfma_f32_16x16x32_bf16 v[104:107], v[136:139], v[152:155], v[104:107]
	v_mfma_f32_16x16x32_bf16 v[100:103], v[128:131], v[160:163], v[100:103]
	v_mfma_f32_16x16x32_bf16 v[88:91], v[136:139], v[160:163], v[88:91]
	v_mfma_f32_16x16x32_bf16 v[84:87], v[128:131], v[168:171], v[84:87]
	v_mfma_f32_16x16x32_bf16 v[72:75], v[136:139], v[168:171], v[72:75]
	v_mfma_f32_16x16x32_bf16 v[124:127], v[132:135], v[148:151], v[124:127]
	v_mfma_f32_16x16x32_bf16 v[120:123], v[140:143], v[148:151], v[120:123]
	v_mfma_f32_16x16x32_bf16 v[116:119], v[132:135], v[156:159], v[116:119]
	v_mfma_f32_16x16x32_bf16 v[104:107], v[140:143], v[156:159], v[104:107]
	v_mfma_f32_16x16x32_bf16 v[100:103], v[132:135], v[164:167], v[100:103]
	v_mfma_f32_16x16x32_bf16 v[88:91], v[140:143], v[164:167], v[88:91]
	v_mfma_f32_16x16x32_bf16 v[84:87], v[132:135], v[172:175], v[84:87]
	v_mfma_f32_16x16x32_bf16 v[72:75], v[140:143], v[172:175], v[72:75]
	s_barrier
	s_add_i32 s76, 0, 0x1c000
	s_add_i32 s77, s78, s27
	v_add_u32_e32 v180, s76, v189
	v_lshl_add_u64 v[224:225], v[224:225], 0, s[30:31]
	s_mov_b32 m0, s77
	ds_read_b128 v[208:211], v180
	ds_read_b128 v[212:215], v180 offset:1024
	ds_read_b128 v[216:219], v180 offset:2048
	ds_read_b128 v[220:223], v180 offset:3072
	global_load_lds_dwordx4 v[224:225], off
	v_lshl_add_u64 v[224:225], v[226:227], 0, s[30:31]
	s_add_i32 m0, s77, 0x2000
	s_nop 0
	global_load_lds_dwordx4 v[224:225], off
	s_barrier
	s_waitcnt lgkmcnt(0)
	s_waitcnt lgkmcnt(0)
	v_mfma_f32_16x16x32_bf16 v[112:115], v[208:211], v[144:147], v[112:115]
	v_mfma_f32_16x16x32_bf16 v[108:111], v[216:219], v[144:147], v[108:111]
	v_mfma_f32_16x16x32_bf16 v[96:99], v[208:211], v[152:155], v[96:99]
	v_mfma_f32_16x16x32_bf16 v[92:95], v[216:219], v[152:155], v[92:95]
	v_mfma_f32_16x16x32_bf16 v[80:83], v[208:211], v[160:163], v[80:83]
	v_mfma_f32_16x16x32_bf16 v[76:79], v[216:219], v[160:163], v[76:79]
	v_mfma_f32_16x16x32_bf16 v[68:71], v[208:211], v[168:171], v[68:71]
	v_mfma_f32_16x16x32_bf16 v[64:67], v[216:219], v[168:171], v[64:67]
	v_mfma_f32_16x16x32_bf16 v[112:115], v[212:215], v[148:151], v[112:115]
	v_mfma_f32_16x16x32_bf16 v[108:111], v[220:223], v[148:151], v[108:111]
	v_mfma_f32_16x16x32_bf16 v[96:99], v[212:215], v[156:159], v[96:99]
	v_mfma_f32_16x16x32_bf16 v[92:95], v[220:223], v[156:159], v[92:95]
	v_mfma_f32_16x16x32_bf16 v[80:83], v[212:215], v[164:167], v[80:83]
	v_mfma_f32_16x16x32_bf16 v[76:79], v[220:223], v[164:167], v[76:79]
	v_mfma_f32_16x16x32_bf16 v[68:71], v[212:215], v[172:175], v[68:71]
	v_mfma_f32_16x16x32_bf16 v[64:67], v[220:223], v[172:175], v[64:67]
	s_mov_b32 m0, s62
	v_lshl_add_u64 v[224:225], v[228:229], 0, s[30:31]
	s_barrier
	ds_read_b128 v[144:147], v197 offset:49152
	ds_read_b128 v[148:151], v197 offset:50176
	ds_read_b128 v[152:155], v197 offset:51200
	ds_read_b128 v[156:159], v197 offset:52224
	ds_read_b128 v[160:163], v197 offset:53248
	ds_read_b128 v[164:167], v197 offset:54272
	ds_read_b128 v[168:171], v197 offset:55296
	ds_read_b128 v[172:175], v197 offset:56320
	global_load_lds_dwordx4 v[224:225], off
	v_lshl_add_u64 v[224:225], v[242:243], 0, s[30:31]
	s_mov_b32 m0, s63
	s_nop 0
	global_load_lds_dwordx4 v[224:225], off
	s_barrier
; #define PG8_STAGE(bufoff, gbase, voff) do { _Pragma("unroll") for (int _i = 0; _i < 2; ++_i) \
;         __builtin_amdgcn_global_load_lds((const unsigned*)((const char*)(gbase) + (voff)[_i]), (LAS unsigned*)(lds + (bufoff) + ldsw + _i * 8192), 16, 0, 0); } while (0)
; #define PG8_LDA(dst, b, h) do { _Pragma("unroll") for (int m = 0; m < 4; ++m) _Pragma("unroll") for (int k = 0; k < 2; ++k) dst[m][k] = *(const LAS bf16x8*)(lds + PG8_SA(b, h) + aoff + m * 2048 + k * 1024); } while (0)
; #define PG8_LDB(dst, b, h) do { _Pragma("unroll") for (int n = 0; n < 2; ++n) _Pragma("unroll") for (int k = 0; k < 2; ++k) dst[n][k] = *(const LAS bf16x8*)(lds + PG8_SB(b, h) + boff + n * 2048 + k * 1024); } while (0)
; #define PG8_WAIT_V(n) asm volatile("s_waitcnt vmcnt(" #n ")" ::: "memory")
; template <class F>
; DI void gemm_phase(const int tid, LAS unsigned char* lds, const bf16_t* Ap, int lda, const bf16_t* Bp, int ldb, int M, int N, int K, int G, int c, bool direct, const F& E) {
;     ...
;             PG8_WAIT_V(6); PG8_BAR; PG8_MMA(1, 1, At, B1); PG8_BAR;
;             PG8_LDB(B0, 1, 0); PG8_SCHED; PG8_LDA(At, 1, 0); PG8_STAGE(PG8_SA(0, 1), a2 + hsA, voffA);
;             PG8_WAIT_L(8); PG8_BAR; PG8_WAIT_L(0); PG8_MMA(0, 0, At, B0); PG8_BAR; PG8_SCHED;
;             PG8_LDB(B1, 1, 1); PG8_STAGE(PG8_SB(1, 0), b3, voffB);
;             PG8_BAR; PG8_WAIT_L(0); PG8_MMA(0, 1, At, B1); PG8_BAR;
;             PG8_LDA(At, 1, 1); PG8_STAGE(PG8_SA(1, 0), a3, voffA);
;             PG8_BAR; PG8_WAIT_L(0); PG8_MMA(1, 0, At, B0); PG8_BAR; PG8_SCHED;
;             PG8_STAGE(PG8_SB(1, 1), b3 + hsB, voffB);
;             PG8_WAIT_V(6); PG8_BAR; PG8_MMA(1, 1, At, B1); PG8_BAR;
;         }
;         if (E.kind == 7  ) E.fused(acc, cur.pm, cur.pn, wr, wc, fr, fq);
; DI void Epi::fused(const f32x4 (&acc)[2][2][4][2], int pm, int pn, int wr, int wc, int fr, int fq) const {
;     ...
;         const int ncol = pn * 256 + bj * 128 + wc * 32 + 8 * fq, j0 = (ncol >> 3) * 4;
;         const f32x4 wa0 = *(const f32x4*)(E.cf0 + j0), wa1 = *(const f32x4*)(E.cf0 + FF2 + j0), wa2 = *(const f32x4*)(E.cf0 + 2 * FF2 + j0);
;         const f32x4 wb0 = *(const f32x4*)(E.cf0 + FFH + j0), wb1 = *(const f32x4*)(E.cf0 + FF2 + FFH + j0), wb2 = *(const f32x4*)(E.cf0 + 2 * FF2 + FFH + j0);
;         const f32x4 ba = *(const f32x4*)(E.cf1 + j0), bb = *(const f32x4*)(E.cf1 + FFH + j0);
	s_waitcnt lgkmcnt(0)
	s_waitcnt lgkmcnt(0)
	v_mfma_f32_16x16x32_bf16 v[60:63], v[128:131], v[144:147], v[60:63]
	v_mfma_f32_16x16x32_bf16 v[56:59], v[136:139], v[144:147], v[56:59]
	v_mfma_f32_16x16x32_bf16 v[52:55], v[128:131], v[152:155], v[52:55]
	v_mfma_f32_16x16x32_bf16 v[40:43], v[136:139], v[152:155], v[40:43]
	v_mfma_f32_16x16x32_bf16 v[36:39], v[128:131], v[160:163], v[36:39]
	v_mfma_f32_16x16x32_bf16 v[16:19], v[136:139], v[160:163], v[16:19]
	v_mfma_f32_16x16x32_bf16 v[12:15], v[128:131], v[168:171], v[12:15]
	v_mfma_f32_16x16x32_bf16 v[0:3], v[136:139], v[168:171], v[0:3]
	v_mfma_f32_16x16x32_bf16 v[60:63], v[132:135], v[148:151], v[60:63]
	v_mfma_f32_16x16x32_bf16 v[56:59], v[140:143], v[148:151], v[56:59]
	v_mfma_f32_16x16x32_bf16 v[52:55], v[132:135], v[156:159], v[52:55]
	v_mfma_f32_16x16x32_bf16 v[40:43], v[140:143], v[156:159], v[40:43]
	v_mfma_f32_16x16x32_bf16 v[36:39], v[132:135], v[164:167], v[36:39]
	v_mfma_f32_16x16x32_bf16 v[16:19], v[140:143], v[164:167], v[16:19]
	v_mfma_f32_16x16x32_bf16 v[12:15], v[132:135], v[172:175], v[12:15]
	v_mfma_f32_16x16x32_bf16 v[0:3], v[140:143], v[172:175], v[0:3]
	s_barrier
	s_add_i32 s76, s76, s27
	v_lshl_add_u64 v[128:129], v[244:245], 0, s[30:31]
	s_mov_b32 m0, s76
	s_nop 0
	global_load_lds_dwordx4 v[128:129], off
	v_lshl_add_u64 v[128:129], v[246:247], 0, s[30:31]
	s_add_i32 m0, s76, 0x2000
	s_nop 0
	global_load_lds_dwordx4 v[128:129], off
	s_waitcnt vmcnt(6)
	s_barrier
	v_mfma_f32_16x16x32_bf16 v[48:51], v[208:211], v[144:147], v[48:51]
	v_mfma_f32_16x16x32_bf16 v[44:47], v[216:219], v[144:147], v[44:47]
	v_mfma_f32_16x16x32_bf16 v[24:27], v[208:211], v[152:155], v[24:27]
	v_mfma_f32_16x16x32_bf16 v[20:23], v[216:219], v[152:155], v[20:23]
	v_mfma_f32_16x16x32_bf16 v[28:31], v[208:211], v[160:163], v[28:31]
	v_mfma_f32_16x16x32_bf16 v[32:35], v[216:219], v[160:163], v[32:35]
	v_mfma_f32_16x16x32_bf16 v[8:11], v[208:211], v[168:171], v[8:11]
	v_mfma_f32_16x16x32_bf16 v[4:7], v[216:219], v[168:171], v[4:7]
	v_mfma_f32_16x16x32_bf16 v[48:51], v[212:215], v[148:151], v[48:51]
	v_mfma_f32_16x16x32_bf16 v[44:47], v[220:223], v[148:151], v[44:47]
	v_mfma_f32_16x16x32_bf16 v[24:27], v[212:215], v[156:159], v[24:27]
	v_mfma_f32_16x16x32_bf16 v[20:23], v[220:223], v[156:159], v[20:23]
	v_mfma_f32_16x16x32_bf16 v[28:31], v[212:215], v[164:167], v[28:31]
	v_mfma_f32_16x16x32_bf16 v[32:35], v[220:223], v[164:167], v[32:35]
	v_mfma_f32_16x16x32_bf16 v[8:11], v[212:215], v[172:175], v[8:11]
	v_mfma_f32_16x16x32_bf16 v[4:7], v[220:223], v[172:175], v[4:7]
	s_add_u32 s74, s74, 0x100
	s_addc_u32 s75, s75, 0
	s_add_u32 s71, s71, 0x100
	s_addc_u32 s80, s80, 0
	s_cmp_ge_u32 s81, s26
	s_mov_b32 s76, s81
	s_barrier
	s_cbranch_scc0 .LBB0_657
	s_mov_b64 s[76:77], -1
	s_mov_b64 s[74:75], 0
	s_cmp_lt_i32 s92, 3
	s_mov_b64 s[78:79], 0
	s_cbranch_scc1 .LBB0_688
	s_cmp_gt_i32 s92, 6
	s_mov_b64 s[78:79], -1
	s_cbranch_scc0 .LBB0_685
	v_lshl_or_b32 v240, s70, 8, v194
	v_mov_b32_e32 v241, 0
	s_lshl_b32 s71, s36, 8
	v_readlane_b32 s76, v255, 16
	s_nop 3
	s_add_i32 s71, s71, s76
	v_or_b32_e32 v199, s71, v188
	v_lshlrev_b32_e32 v238, 1, v240
	v_mov_b32_e32 v239, 0
	v_lshl_add_u64 v[136:137], s[22:23], 0, v[238:239]
	global_load_dwordx4 v[136:139], v[136:137], off
	v_readlane_b32 s76, v254, 54
	v_readlane_b32 s77, v254, 55
	s_nop 1
	v_lshl_add_u64 v[140:141], s[76:77], 0, v[238:239]
	global_load_dwordx4 v[140:143], v[140:141], off
	v_readlane_b32 s76, v254, 56
	v_readlane_b32 s77, v254, 57
	s_nop 1
	v_lshl_add_u64 v[152:153], s[76:77], 0, v[238:239]
	global_load_dwordx4 v[152:155], v[152:153], off
	v_readlane_b32 s76, v255, 4
	v_readlane_b32 s77, v255, 5
	s_nop 1
	v_lshl_add_u64 v[128:129], s[76:77], 0, v[238:239]
	global_load_dwordx4 v[128:131], v[128:129], off
	v_readlane_b32 s76, v255, 6
	v_readlane_b32 s77, v255, 7
	s_nop 1
	v_lshl_add_u64 v[132:133], s[76:77], 0, v[238:239]
	global_load_dwordx4 v[132:135], v[132:133], off
	v_readlane_b32 s76, v255, 8
	v_readlane_b32 s77, v255, 9
	s_nop 1
	v_lshl_add_u64 v[144:145], s[76:77], 0, v[238:239]
	global_load_dwordx4 v[144:147], v[144:145], off
	v_readlane_b32 s76, v254, 49
	v_readlane_b32 s77, v254, 50
	s_nop 1
	v_lshl_add_u64 v[156:157], s[76:77], 0, v[238:239]
	global_load_dwordx4 v[156:159], v[156:157], off
	v_lshl_add_u64 v[148:149], s[72:73], 0, v[238:239]
	global_load_dwordx4 v[148:151], v[148:149], off
	v_mov_b32_e32 v228, v199
	v_mov_b64_e32 v[224:225], s[12:13]
	s_movk_i32 s80, 0x1600
	v_mad_i64_i32 v[224:225], s[78:79], v228, s80, v[224:225]
	v_mov_b32_e32 v228, v240
	v_mov_b32_e32 v229, 0
	v_lshl_add_u64 v[224:225], v[228:229], 0, v[224:225]
	s_waitcnt vmcnt(0)
; DI float silu_fast(float x) { return x * __builtin_amdgcn_rcpf(1.f + __expf(-x)); }
; template <int CTRL> DI float dppf(float v) { return __builtin_bit_cast(float, __builtin_amdgcn_update_dpp(0, __builtin_bit_cast(int, v), CTRL, 0xf, 0xf, true)); }
; DI void Epi::fused(const f32x4 (&acc)[2][2][4][2], int pm, int pn, int wr, int wc, int fr, int fq) const {
;     ...
;             for (int m = 0; m < 4; ++m) {
;                 const f32x4 ca = acc[ai][bj][m][0], cb = acc[ai][bj][m][1];
;                 const int row = pm * 256 + ai * 128 + wr * 64 + m * 16 + fr;
;                 float o[4];
; #pragma unroll
;                 for (int e = 0; e < 4; ++e) {
;                     const float a1 = dppf<0x111>(ca[e]) + dppf<0x10F>(pa[e]), a2 = dppf<0x112>(ca[e]) + dppf<0x10E>(pa[e]);
;                     const float b1 = dppf<0x111>(cb[e]) + dppf<0x10F>(pb[e]), b2 = dppf<0x112>(cb[e]) + dppf<0x10E>(pb[e]);
;                     const float ya = fmaf(wa0[e], a2, fmaf(wa1[e], a1, fmaf(wa2[e], ca[e], ba[e])));
;                     const float yb = fmaf(wb0[e], b2, fmaf(wb1[e], b1, fmaf(wb2[e], cb[e], bb[e])));
;                     o[e] = silu_fast(ya) * yb; }
;                 if (m > 0 || fr >= 2) { u32x2 w; w.x = pk2(o[0], o[1]); w.y = pk2(o[2], o[3]); *(u32x2*)(E.d0 + (size_t)row * FFH + j0) = w; }
;                 if ((m == 0 && fr < 2) || (m == 3 && fr >= 14)) { float* hb = E.f0 + ((size_t)(row >> 6) * 4 + (m == 0 ? fr : fr - 12)) * FF2 + ncol; *(f32x4*)hb = ca; *(f32x4*)(hb + 4) = cb; }
;                 pa = ca; pb = cb;
	v_fma_f32 v160, v152, v124, v156
	v_fma_f32 v161, v153, v125, v157
	v_fma_f32 v162, v154, v126, v158
	v_fma_f32 v163, v155, v127, v159
	v_fma_f32 v164, v144, v120, v148
	v_fma_f32 v165, v145, v121, v149
	v_fma_f32 v166, v146, v122, v150
	v_fma_f32 v167, v147, v123, v151
	v_fmac_f32_dpp v160, v124, v140 row_shr:1 row_mask:0xf bank_mask:0xf
	v_fmac_f32_dpp v161, v125, v141 row_shr:1 row_mask:0xf bank_mask:0xf
	v_fmac_f32_dpp v162, v126, v142 row_shr:1 row_mask:0xf bank_mask:0xf
	v_fmac_f32_dpp v163, v127, v143 row_shr:1 row_mask:0xf bank_mask:0xf
	v_fmac_f32_dpp v164, v120, v132 row_shr:1 row_mask:0xf bank_mask:0xf
	v_fmac_f32_dpp v165, v121, v133 row_shr:1 row_mask:0xf bank_mask:0xf
	v_fmac_f32_dpp v166, v122, v134 row_shr:1 row_mask:0xf bank_mask:0xf
	v_fmac_f32_dpp v167, v123, v135 row_shr:1 row_mask:0xf bank_mask:0xf
	v_fmac_f32_dpp v160, v124, v136 row_shr:2 row_mask:0xf bank_mask:0xf
	v_fmac_f32_dpp v161, v125, v137 row_shr:2 row_mask:0xf bank_mask:0xf
	v_fmac_f32_dpp v162, v126, v138 row_shr:2 row_mask:0xf bank_mask:0xf
	v_fmac_f32_dpp v163, v127, v139 row_shr:2 row_mask:0xf bank_mask:0xf
	v_fmac_f32_dpp v164, v120, v128 row_shr:2 row_mask:0xf bank_mask:0xf
	v_fmac_f32_dpp v165, v121, v129 row_shr:2 row_mask:0xf bank_mask:0xf
	v_fmac_f32_dpp v166, v122, v130 row_shr:2 row_mask:0xf bank_mask:0xf
	v_fmac_f32_dpp v167, v123, v131 row_shr:2 row_mask:0xf bank_mask:0xf
	v_mul_f32_e32 v168, 0xbfb8aa3b, v160
	v_mul_f32_e32 v169, 0xbfb8aa3b, v161
	v_mul_f32_e32 v170, 0xbfb8aa3b, v162
	v_mul_f32_e32 v171, 0xbfb8aa3b, v163
	v_exp_f32_e32 v168, v168
	v_exp_f32_e32 v169, v169
	v_exp_f32_e32 v170, v170
	v_exp_f32_e32 v171, v171
	v_add_f32_e32 v168, 1.0, v168
	v_add_f32_e32 v169, 1.0, v169
	v_add_f32_e32 v170, 1.0, v170
	v_add_f32_e32 v171, 1.0, v171
	v_rcp_f32_e32 v168, v168
	v_rcp_f32_e32 v169, v169
	v_rcp_f32_e32 v170, v170
	v_rcp_f32_e32 v171, v171
	v_mov_b64_e32 v[174:175], v[224:225]
	v_mul_f32_e32 v160, v160, v168
	v_mul_f32_e32 v161, v161, v169
	v_mul_f32_e32 v162, v162, v170
	v_mul_f32_e32 v163, v163, v171
	v_mul_f32_e32 v160, v164, v160
	v_mul_f32_e32 v161, v165, v161
	v_mul_f32_e32 v162, v166, v162
	v_mul_f32_e32 v163, v167, v163
	v_cvt_pk_bf16_f32 v172, v160, v161
	v_cvt_pk_bf16_f32 v173, v162, v163
	s_and_saveexec_b64 s[76:77], s[38:39]
	global_store_dwordx2 v[174:175], v[172:173], off
	s_or_b64 exec, exec, s[76:77]
	s_ashr_i32 s80, s71, 6
	s_lshl_b32 s80, s80, 2
	v_add_u32_e32 v226, s80, v188
	v_mov_b64_e32 v[174:175], s[8:9]
	s_movk_i32 s80, 0x5800
	v_mad_i64_i32 v[174:175], s[78:79], v226, s80, v[174:175]
	v_lshl_add_u64 v[174:175], v[228:229], 2, v[174:175]
	s_and_saveexec_b64 s[76:77], s[40:41]
	global_store_dwordx4 v[174:175], v[124:127], off
	global_store_dwordx4 v[174:175], v[120:123], off offset:16
	s_or_b64 exec, exec, s[76:77]
	v_fma_f32 v208, v152, v116, v156
	v_fma_f32 v209, v153, v117, v157
	v_fma_f32 v210, v154, v118, v158
	v_fma_f32 v211, v155, v119, v159
	v_fma_f32 v212, v144, v104, v148
	v_fma_f32 v213, v145, v105, v149
	v_fma_f32 v214, v146, v106, v150
	v_fma_f32 v215, v147, v107, v151
	v_fmac_f32_dpp v208, v116, v140 row_shr:1 row_mask:0xf bank_mask:0xf
	v_fmac_f32_dpp v209, v117, v141 row_shr:1 row_mask:0xf bank_mask:0xf
	v_fmac_f32_dpp v210, v118, v142 row_shr:1 row_mask:0xf bank_mask:0xf
	v_fmac_f32_dpp v211, v119, v143 row_shr:1 row_mask:0xf bank_mask:0xf
	v_fmac_f32_dpp v212, v104, v132 row_shr:1 row_mask:0xf bank_mask:0xf
	v_fmac_f32_dpp v213, v105, v133 row_shr:1 row_mask:0xf bank_mask:0xf
	v_fmac_f32_dpp v214, v106, v134 row_shr:1 row_mask:0xf bank_mask:0xf
	v_fmac_f32_dpp v215, v107, v135 row_shr:1 row_mask:0xf bank_mask:0xf
	v_fmac_f32_dpp v208, v124, v140 row_shl:15 row_mask:0xf bank_mask:0xf
	v_fmac_f32_dpp v209, v125, v141 row_shl:15 row_mask:0xf bank_mask:0xf
	v_fmac_f32_dpp v210, v126, v142 row_shl:15 row_mask:0xf bank_mask:0xf
	v_fmac_f32_dpp v211, v127, v143 row_shl:15 row_mask:0xf bank_mask:0xf
	v_fmac_f32_dpp v212, v120, v132 row_shl:15 row_mask:0xf bank_mask:0xf
	v_fmac_f32_dpp v213, v121, v133 row_shl:15 row_mask:0xf bank_mask:0xf
	v_fmac_f32_dpp v214, v122, v134 row_shl:15 row_mask:0xf bank_mask:0xf
	v_fmac_f32_dpp v215, v123, v135 row_shl:15 row_mask:0xf bank_mask:0xf
	v_fmac_f32_dpp v208, v116, v136 row_shr:2 row_mask:0xf bank_mask:0xf
	v_fmac_f32_dpp v209, v117, v137 row_shr:2 row_mask:0xf bank_mask:0xf
	v_fmac_f32_dpp v210, v118, v138 row_shr:2 row_mask:0xf bank_mask:0xf
	v_fmac_f32_dpp v211, v119, v139 row_shr:2 row_mask:0xf bank_mask:0xf
	v_fmac_f32_dpp v212, v104, v128 row_shr:2 row_mask:0xf bank_mask:0xf
	v_fmac_f32_dpp v213, v105, v129 row_shr:2 row_mask:0xf bank_mask:0xf
	v_fmac_f32_dpp v214, v106, v130 row_shr:2 row_mask:0xf bank_mask:0xf
	v_fmac_f32_dpp v215, v107, v131 row_shr:2 row_mask:0xf bank_mask:0xf
	v_fmac_f32_dpp v208, v124, v136 row_shl:14 row_mask:0xf bank_mask:0xf
	v_fmac_f32_dpp v209, v125, v137 row_shl:14 row_mask:0xf bank_mask:0xf
	v_fmac_f32_dpp v210, v126, v138 row_shl:14 row_mask:0xf bank_mask:0xf
	v_fmac_f32_dpp v211, v127, v139 row_shl:14 row_mask:0xf bank_mask:0xf
	v_fmac_f32_dpp v212, v120, v128 row_shl:14 row_mask:0xf bank_mask:0xf
	v_fmac_f32_dpp v213, v121, v129 row_shl:14 row_mask:0xf bank_mask:0xf
	v_fmac_f32_dpp v214, v122, v130 row_shl:14 row_mask:0xf bank_mask:0xf
	v_fmac_f32_dpp v215, v123, v131 row_shl:14 row_mask:0xf bank_mask:0xf
	v_mul_f32_e32 v216, 0xbfb8aa3b, v208
	v_mul_f32_e32 v217, 0xbfb8aa3b, v209
	v_mul_f32_e32 v218, 0xbfb8aa3b, v210
	v_mul_f32_e32 v219, 0xbfb8aa3b, v211
	v_exp_f32_e32 v216, v216
	v_exp_f32_e32 v217, v217
	v_exp_f32_e32 v218, v218
	v_exp_f32_e32 v219, v219
	v_add_f32_e32 v216, 1.0, v216
	v_add_f32_e32 v217, 1.0, v217
; DI float silu_fast(float x) { return x * __builtin_amdgcn_rcpf(1.f + __expf(-x)); }
; template <int CTRL> DI float dppf(float v) { return __builtin_bit_cast(float, __builtin_amdgcn_update_dpp(0, __builtin_bit_cast(int, v), CTRL, 0xf, 0xf, true)); }
; DI void Epi::fused(const f32x4 (&acc)[2][2][4][2], int pm, int pn, int wr, int wc, int fr, int fq) const {
;     ...
;             for (int m = 0; m < 4; ++m) {
;                 const f32x4 ca = acc[ai][bj][m][0], cb = acc[ai][bj][m][1];
;                 const int row = pm * 256 + ai * 128 + wr * 64 + m * 16 + fr;
;                 float o[4];
; #pragma unroll
;                 for (int e = 0; e < 4; ++e) {
;                     const float a1 = dppf<0x111>(ca[e]) + dppf<0x10F>(pa[e]), a2 = dppf<0x112>(ca[e]) + dppf<0x10E>(pa[e]);
;                     const float b1 = dppf<0x111>(cb[e]) + dppf<0x10F>(pb[e]), b2 = dppf<0x112>(cb[e]) + dppf<0x10E>(pb[e]);
;                     const float ya = fmaf(wa0[e], a2, fmaf(wa1[e], a1, fmaf(wa2[e], ca[e], ba[e])));
;                     const float yb = fmaf(wb0[e], b2, fmaf(wb1[e], b1, fmaf(wb2[e], cb[e], bb[e])));
;                     o[e] = silu_fast(ya) * yb; }
;                 if (m > 0 || fr >= 2) { u32x2 w; w.x = pk2(o[0], o[1]); w.y = pk2(o[2], o[3]); *(u32x2*)(E.d0 + (size_t)row * FFH + j0) = w; }
;                 if ((m == 0 && fr < 2) || (m == 3 && fr >= 14)) { float* hb = E.f0 + ((size_t)(row >> 6) * 4 + (m == 0 ? fr : fr - 12)) * FF2 + ncol; *(f32x4*)hb = ca; *(f32x4*)(hb + 4) = cb; }
;                 pa = ca; pb = cb;
	v_add_f32_e32 v218, 1.0, v218
	v_add_f32_e32 v219, 1.0, v219
	v_rcp_f32_e32 v216, v216
	v_rcp_f32_e32 v217, v217
	v_rcp_f32_e32 v218, v218
	v_rcp_f32_e32 v219, v219
	s_mov_b32 s80, 0x16000
	s_mov_b32 s81, 0
	v_lshl_add_u64 v[222:223], v[224:225], 0, s[80:81]
	v_mul_f32_e32 v208, v208, v216
	v_mul_f32_e32 v209, v209, v217
	v_mul_f32_e32 v210, v210, v218
	v_mul_f32_e32 v211, v211, v219
	v_mul_f32_e32 v208, v212, v208
	v_mul_f32_e32 v209, v213, v209
	v_mul_f32_e32 v210, v214, v210
	v_mul_f32_e32 v211, v215, v211
	v_cvt_pk_bf16_f32 v220, v208, v209
	v_cvt_pk_bf16_f32 v221, v210, v211
	global_store_dwordx2 v[222:223], v[220:221], off
	v_fma_f32 v160, v152, v100, v156
	v_fma_f32 v161, v153, v101, v157
	v_fma_f32 v162, v154, v102, v158
	v_fma_f32 v163, v155, v103, v159
	v_fma_f32 v164, v144, v88, v148
	v_fma_f32 v165, v145, v89, v149
	v_fma_f32 v166, v146, v90, v150
	v_fma_f32 v167, v147, v91, v151
	v_fmac_f32_dpp v160, v100, v140 row_shr:1 row_mask:0xf bank_mask:0xf
	v_fmac_f32_dpp v161, v101, v141 row_shr:1 row_mask:0xf bank_mask:0xf
	v_fmac_f32_dpp v162, v102, v142 row_shr:1 row_mask:0xf bank_mask:0xf
	v_fmac_f32_dpp v163, v103, v143 row_shr:1 row_mask:0xf bank_mask:0xf
	v_fmac_f32_dpp v164, v88, v132 row_shr:1 row_mask:0xf bank_mask:0xf
	v_fmac_f32_dpp v165, v89, v133 row_shr:1 row_mask:0xf bank_mask:0xf
	v_fmac_f32_dpp v166, v90, v134 row_shr:1 row_mask:0xf bank_mask:0xf
	v_fmac_f32_dpp v167, v91, v135 row_shr:1 row_mask:0xf bank_mask:0xf
	v_fmac_f32_dpp v160, v116, v140 row_shl:15 row_mask:0xf bank_mask:0xf
	v_fmac_f32_dpp v161, v117, v141 row_shl:15 row_mask:0xf bank_mask:0xf
	v_fmac_f32_dpp v162, v118, v142 row_shl:15 row_mask:0xf bank_mask:0xf
	v_fmac_f32_dpp v163, v119, v143 row_shl:15 row_mask:0xf bank_mask:0xf
	v_fmac_f32_dpp v164, v104, v132 row_shl:15 row_mask:0xf bank_mask:0xf
	v_fmac_f32_dpp v165, v105, v133 row_shl:15 row_mask:0xf bank_mask:0xf
	v_fmac_f32_dpp v166, v106, v134 row_shl:15 row_mask:0xf bank_mask:0xf
	v_fmac_f32_dpp v167, v107, v135 row_shl:15 row_mask:0xf bank_mask:0xf
	v_fmac_f32_dpp v160, v100, v136 row_shr:2 row_mask:0xf bank_mask:0xf
	v_fmac_f32_dpp v161, v101, v137 row_shr:2 row_mask:0xf bank_mask:0xf
	v_fmac_f32_dpp v162, v102, v138 row_shr:2 row_mask:0xf bank_mask:0xf
	v_fmac_f32_dpp v163, v103, v139 row_shr:2 row_mask:0xf bank_mask:0xf
	v_fmac_f32_dpp v164, v88, v128 row_shr:2 row_mask:0xf bank_mask:0xf
	v_fmac_f32_dpp v165, v89, v129 row_shr:2 row_mask:0xf bank_mask:0xf
	v_fmac_f32_dpp v166, v90, v130 row_shr:2 row_mask:0xf bank_mask:0xf
	v_fmac_f32_dpp v167, v91, v131 row_shr:2 row_mask:0xf bank_mask:0xf
	v_fmac_f32_dpp v160, v116, v136 row_shl:14 row_mask:0xf bank_mask:0xf
	v_fmac_f32_dpp v161, v117, v137 row_shl:14 row_mask:0xf bank_mask:0xf
	v_fmac_f32_dpp v162, v118, v138 row_shl:14 row_mask:0xf bank_mask:0xf
	v_fmac_f32_dpp v163, v119, v139 row_shl:14 row_mask:0xf bank_mask:0xf
	v_fmac_f32_dpp v164, v104, v128 row_shl:14 row_mask:0xf bank_mask:0xf
	v_fmac_f32_dpp v165, v105, v129 row_shl:14 row_mask:0xf bank_mask:0xf
	v_fmac_f32_dpp v166, v106, v130 row_shl:14 row_mask:0xf bank_mask:0xf
	v_fmac_f32_dpp v167, v107, v131 row_shl:14 row_mask:0xf bank_mask:0xf
	v_mul_f32_e32 v168, 0xbfb8aa3b, v160
	v_mul_f32_e32 v169, 0xbfb8aa3b, v161
	v_mul_f32_e32 v170, 0xbfb8aa3b, v162
	v_mul_f32_e32 v171, 0xbfb8aa3b, v163
	v_exp_f32_e32 v168, v168
	v_exp_f32_e32 v169, v169
	v_exp_f32_e32 v170, v170
	v_exp_f32_e32 v171, v171
	v_add_f32_e32 v168, 1.0, v168
	v_add_f32_e32 v169, 1.0, v169
	v_add_f32_e32 v170, 1.0, v170
	v_add_f32_e32 v171, 1.0, v171
	v_rcp_f32_e32 v168, v168
	v_rcp_f32_e32 v169, v169
	v_rcp_f32_e32 v170, v170
	v_rcp_f32_e32 v171, v171
	s_mov_b32 s80, 0x2c000
	s_mov_b32 s81, 0
	v_lshl_add_u64 v[174:175], v[224:225], 0, s[80:81]
	v_mul_f32_e32 v160, v160, v168
	v_mul_f32_e32 v161, v161, v169
	v_mul_f32_e32 v162, v162, v170
	v_mul_f32_e32 v163, v163, v171
	v_mul_f32_e32 v160, v164, v160
	v_mul_f32_e32 v161, v165, v161
	v_mul_f32_e32 v162, v166, v162
	v_mul_f32_e32 v163, v167, v163
	v_cvt_pk_bf16_f32 v172, v160, v161
	v_cvt_pk_bf16_f32 v173, v162, v163
	global_store_dwordx2 v[174:175], v[172:173], off
	v_fma_f32 v208, v152, v84, v156
	v_fma_f32 v209, v153, v85, v157
	v_fma_f32 v210, v154, v86, v158
	v_fma_f32 v211, v155, v87, v159
	v_fma_f32 v212, v144, v72, v148
	v_fma_f32 v213, v145, v73, v149
	v_fma_f32 v214, v146, v74, v150
	v_fma_f32 v215, v147, v75, v151
	v_fmac_f32_dpp v208, v84, v140 row_shr:1 row_mask:0xf bank_mask:0xf
	v_fmac_f32_dpp v209, v85, v141 row_shr:1 row_mask:0xf bank_mask:0xf
	v_fmac_f32_dpp v210, v86, v142 row_shr:1 row_mask:0xf bank_mask:0xf
	v_fmac_f32_dpp v211, v87, v143 row_shr:1 row_mask:0xf bank_mask:0xf
	v_fmac_f32_dpp v212, v72, v132 row_shr:1 row_mask:0xf bank_mask:0xf
	v_fmac_f32_dpp v213, v73, v133 row_shr:1 row_mask:0xf bank_mask:0xf
	v_fmac_f32_dpp v214, v74, v134 row_shr:1 row_mask:0xf bank_mask:0xf
	v_fmac_f32_dpp v215, v75, v135 row_shr:1 row_mask:0xf bank_mask:0xf
	v_fmac_f32_dpp v208, v100, v140 row_shl:15 row_mask:0xf bank_mask:0xf
	v_fmac_f32_dpp v209, v101, v141 row_shl:15 row_mask:0xf bank_mask:0xf
	v_fmac_f32_dpp v210, v102, v142 row_shl:15 row_mask:0xf bank_mask:0xf
	v_fmac_f32_dpp v211, v103, v143 row_shl:15 row_mask:0xf bank_mask:0xf
	v_fmac_f32_dpp v212, v88, v132 row_shl:15 row_mask:0xf bank_mask:0xf
	v_fmac_f32_dpp v213, v89, v133 row_shl:15 row_mask:0xf bank_mask:0xf
	v_fmac_f32_dpp v214, v90, v134 row_shl:15 row_mask:0xf bank_mask:0xf
	v_fmac_f32_dpp v215, v91, v135 row_shl:15 row_mask:0xf bank_mask:0xf
	v_fmac_f32_dpp v208, v84, v136 row_shr:2 row_mask:0xf bank_mask:0xf
	v_fmac_f32_dpp v209, v85, v137 row_shr:2 row_mask:0xf bank_mask:0xf
; DI float silu_fast(float x) { return x * __builtin_amdgcn_rcpf(1.f + __expf(-x)); }
; template <int CTRL> DI float dppf(float v) { return __builtin_bit_cast(float, __builtin_amdgcn_update_dpp(0, __builtin_bit_cast(int, v), CTRL, 0xf, 0xf, true)); }
; DI void Epi::fused(const f32x4 (&acc)[2][2][4][2], int pm, int pn, int wr, int wc, int fr, int fq) const {
;     ...
;         const int ncol = pn * 256 + bj * 128 + wc * 32 + 8 * fq, j0 = (ncol >> 3) * 4;
;         const f32x4 wa0 = *(const f32x4*)(E.cf0 + j0), wa1 = *(const f32x4*)(E.cf0 + FF2 + j0), wa2 = *(const f32x4*)(E.cf0 + 2 * FF2 + j0);
;         const f32x4 wb0 = *(const f32x4*)(E.cf0 + FFH + j0), wb1 = *(const f32x4*)(E.cf0 + FF2 + FFH + j0), wb2 = *(const f32x4*)(E.cf0 + 2 * FF2 + FFH + j0);
;         const f32x4 ba = *(const f32x4*)(E.cf1 + j0), bb = *(const f32x4*)(E.cf1 + FFH + j0);
;     ...
;             for (int m = 0; m < 4; ++m) {
;                 const f32x4 ca = acc[ai][bj][m][0], cb = acc[ai][bj][m][1];
;                 const int row = pm * 256 + ai * 128 + wr * 64 + m * 16 + fr;
;                 float o[4];
; #pragma unroll
;                 for (int e = 0; e < 4; ++e) {
;                     const float a1 = dppf<0x111>(ca[e]) + dppf<0x10F>(pa[e]), a2 = dppf<0x112>(ca[e]) + dppf<0x10E>(pa[e]);
;                     const float b1 = dppf<0x111>(cb[e]) + dppf<0x10F>(pb[e]), b2 = dppf<0x112>(cb[e]) + dppf<0x10E>(pb[e]);
;                     const float ya = fmaf(wa0[e], a2, fmaf(wa1[e], a1, fmaf(wa2[e], ca[e], ba[e])));
;                     const float yb = fmaf(wb0[e], b2, fmaf(wb1[e], b1, fmaf(wb2[e], cb[e], bb[e])));
;                     o[e] = silu_fast(ya) * yb; }
;                 if (m > 0 || fr >= 2) { u32x2 w; w.x = pk2(o[0], o[1]); w.y = pk2(o[2], o[3]); *(u32x2*)(E.d0 + (size_t)row * FFH + j0) = w; }
;                 if ((m == 0 && fr < 2) || (m == 3 && fr >= 14)) { float* hb = E.f0 + ((size_t)(row >> 6) * 4 + (m == 0 ? fr : fr - 12)) * FF2 + ncol; *(f32x4*)hb = ca; *(f32x4*)(hb + 4) = cb; }
;                 pa = ca; pb = cb;
	v_fmac_f32_dpp v210, v86, v138 row_shr:2 row_mask:0xf bank_mask:0xf
	v_fmac_f32_dpp v211, v87, v139 row_shr:2 row_mask:0xf bank_mask:0xf
	v_fmac_f32_dpp v212, v72, v128 row_shr:2 row_mask:0xf bank_mask:0xf
	v_fmac_f32_dpp v213, v73, v129 row_shr:2 row_mask:0xf bank_mask:0xf
	v_fmac_f32_dpp v214, v74, v130 row_shr:2 row_mask:0xf bank_mask:0xf
	v_fmac_f32_dpp v215, v75, v131 row_shr:2 row_mask:0xf bank_mask:0xf
	v_fmac_f32_dpp v208, v100, v136 row_shl:14 row_mask:0xf bank_mask:0xf
	v_fmac_f32_dpp v209, v101, v137 row_shl:14 row_mask:0xf bank_mask:0xf
	v_fmac_f32_dpp v210, v102, v138 row_shl:14 row_mask:0xf bank_mask:0xf
	v_fmac_f32_dpp v211, v103, v139 row_shl:14 row_mask:0xf bank_mask:0xf
	v_fmac_f32_dpp v212, v88, v128 row_shl:14 row_mask:0xf bank_mask:0xf
	v_fmac_f32_dpp v213, v89, v129 row_shl:14 row_mask:0xf bank_mask:0xf
	v_fmac_f32_dpp v214, v90, v130 row_shl:14 row_mask:0xf bank_mask:0xf
	v_fmac_f32_dpp v215, v91, v131 row_shl:14 row_mask:0xf bank_mask:0xf
	v_mul_f32_e32 v216, 0xbfb8aa3b, v208
	v_mul_f32_e32 v217, 0xbfb8aa3b, v209
	v_mul_f32_e32 v218, 0xbfb8aa3b, v210
	v_mul_f32_e32 v219, 0xbfb8aa3b, v211
	v_exp_f32_e32 v216, v216
	v_exp_f32_e32 v217, v217
	v_exp_f32_e32 v218, v218
	v_exp_f32_e32 v219, v219
	v_add_f32_e32 v216, 1.0, v216
	v_add_f32_e32 v217, 1.0, v217
	v_add_f32_e32 v218, 1.0, v218
	v_add_f32_e32 v219, 1.0, v219
	v_rcp_f32_e32 v216, v216
	v_rcp_f32_e32 v217, v217
	v_rcp_f32_e32 v218, v218
	v_rcp_f32_e32 v219, v219
	s_mov_b32 s80, 0x42000
	s_mov_b32 s81, 0
	v_lshl_add_u64 v[222:223], v[224:225], 0, s[80:81]
	v_mul_f32_e32 v208, v208, v216
	v_mul_f32_e32 v209, v209, v217
	v_mul_f32_e32 v210, v210, v218
	v_mul_f32_e32 v211, v211, v219
	v_mul_f32_e32 v208, v212, v208
	v_mul_f32_e32 v209, v213, v209
	v_mul_f32_e32 v210, v214, v210
	v_mul_f32_e32 v211, v215, v211
	v_cvt_pk_bf16_f32 v220, v208, v209
	v_cvt_pk_bf16_f32 v221, v210, v211
	global_store_dwordx2 v[222:223], v[220:221], off
	s_ashr_i32 s80, s71, 6
	s_lshl_b32 s80, s80, 2
	v_add_u32_e32 v226, s80, v190
	v_mov_b64_e32 v[222:223], s[8:9]
	s_movk_i32 s80, 0x5800
	v_mad_i64_i32 v[222:223], s[78:79], v226, s80, v[222:223]
	v_lshl_add_u64 v[222:223], v[228:229], 2, v[222:223]
	s_and_saveexec_b64 s[76:77], s[42:43]
	global_store_dwordx4 v[222:223], v[84:87], off
	global_store_dwordx4 v[222:223], v[72:75], off offset:16
	s_or_b64 exec, exec, s[76:77]
	v_add_u32_e32 v238, 0x80, v240
	v_lshlrev_b32_e32 v238, 1, v238
	v_mov_b32_e32 v239, 0
	v_lshl_add_u64 v[84:85], s[22:23], 0, v[238:239]
	global_load_dwordx4 v[84:87], v[84:85], off
	v_readlane_b32 s76, v254, 54
	v_readlane_b32 s77, v254, 55
	s_nop 1
	v_lshl_add_u64 v[88:89], s[76:77], 0, v[238:239]
	global_load_dwordx4 v[88:91], v[88:89], off
	v_readlane_b32 s76, v254, 56
	v_readlane_b32 s77, v254, 57
	s_nop 1
	v_lshl_add_u64 v[100:101], s[76:77], 0, v[238:239]
	global_load_dwordx4 v[100:103], v[100:101], off
	v_readlane_b32 s76, v255, 4
	v_readlane_b32 s77, v255, 5
	s_nop 1
	v_lshl_add_u64 v[104:105], s[76:77], 0, v[238:239]
	global_load_dwordx4 v[104:107], v[104:105], off
	v_readlane_b32 s76, v255, 6
	v_readlane_b32 s77, v255, 7
	s_nop 1
	v_lshl_add_u64 v[116:117], s[76:77], 0, v[238:239]
	global_load_dwordx4 v[116:119], v[116:117], off
	v_readlane_b32 s76, v255, 8
	v_readlane_b32 s77, v255, 9
	s_nop 1
	v_lshl_add_u64 v[120:121], s[76:77], 0, v[238:239]
	global_load_dwordx4 v[120:123], v[120:121], off
	v_readlane_b32 s76, v254, 49
	v_readlane_b32 s77, v254, 50
	s_nop 1
	v_lshl_add_u64 v[124:125], s[76:77], 0, v[238:239]
	global_load_dwordx4 v[124:127], v[124:125], off
	v_lshl_add_u64 v[72:73], s[72:73], 0, v[238:239]
	global_load_dwordx4 v[72:75], v[72:73], off
	v_add_u32_e32 v228, 128, v199
	v_mov_b64_e32 v[224:225], s[12:13]
	s_movk_i32 s80, 0x1600
	v_mad_i64_i32 v[224:225], s[78:79], v228, s80, v[224:225]
	v_mov_b32_e32 v228, v240
	v_mov_b32_e32 v229, 0
	v_lshl_add_u64 v[224:225], v[228:229], 0, v[224:225]
	v_fma_f32 v160, v152, v60, v156
	v_fma_f32 v161, v153, v61, v157
	v_fma_f32 v162, v154, v62, v158
	v_fma_f32 v163, v155, v63, v159
	v_fma_f32 v164, v144, v56, v148
	v_fma_f32 v165, v145, v57, v149
	v_fma_f32 v166, v146, v58, v150
	v_fma_f32 v167, v147, v59, v151
	v_fmac_f32_dpp v160, v60, v140 row_shr:1 row_mask:0xf bank_mask:0xf
	v_fmac_f32_dpp v161, v61, v141 row_shr:1 row_mask:0xf bank_mask:0xf
	v_fmac_f32_dpp v162, v62, v142 row_shr:1 row_mask:0xf bank_mask:0xf
	v_fmac_f32_dpp v163, v63, v143 row_shr:1 row_mask:0xf bank_mask:0xf
	v_fmac_f32_dpp v164, v56, v132 row_shr:1 row_mask:0xf bank_mask:0xf
	v_fmac_f32_dpp v165, v57, v133 row_shr:1 row_mask:0xf bank_mask:0xf
	v_fmac_f32_dpp v166, v58, v134 row_shr:1 row_mask:0xf bank_mask:0xf
	v_fmac_f32_dpp v167, v59, v135 row_shr:1 row_mask:0xf bank_mask:0xf
	v_fmac_f32_dpp v160, v60, v136 row_shr:2 row_mask:0xf bank_mask:0xf
	v_fmac_f32_dpp v161, v61, v137 row_shr:2 row_mask:0xf bank_mask:0xf
	v_fmac_f32_dpp v162, v62, v138 row_shr:2 row_mask:0xf bank_mask:0xf
	v_fmac_f32_dpp v163, v63, v139 row_shr:2 row_mask:0xf bank_mask:0xf
	v_fmac_f32_dpp v164, v56, v128 row_shr:2 row_mask:0xf bank_mask:0xf
	v_fmac_f32_dpp v165, v57, v129 row_shr:2 row_mask:0xf bank_mask:0xf
	v_fmac_f32_dpp v166, v58, v130 row_shr:2 row_mask:0xf bank_mask:0xf
	v_fmac_f32_dpp v167, v59, v131 row_shr:2 row_mask:0xf bank_mask:0xf
	v_mul_f32_e32 v168, 0xbfb8aa3b, v160
	v_mul_f32_e32 v169, 0xbfb8aa3b, v161
	v_mul_f32_e32 v170, 0xbfb8aa3b, v162
	v_mul_f32_e32 v171, 0xbfb8aa3b, v163
	v_exp_f32_e32 v168, v168
	v_exp_f32_e32 v169, v169
	v_exp_f32_e32 v170, v170
	v_exp_f32_e32 v171, v171
	v_add_f32_e32 v168, 1.0, v168
	v_add_f32_e32 v169, 1.0, v169
	v_add_f32_e32 v170, 1.0, v170
	v_add_f32_e32 v171, 1.0, v171
; DI float silu_fast(float x) { return x * __builtin_amdgcn_rcpf(1.f + __expf(-x)); }
; template <int CTRL> DI float dppf(float v) { return __builtin_bit_cast(float, __builtin_amdgcn_update_dpp(0, __builtin_bit_cast(int, v), CTRL, 0xf, 0xf, true)); }
; DI void Epi::fused(const f32x4 (&acc)[2][2][4][2], int pm, int pn, int wr, int wc, int fr, int fq) const {
;     ...
;             for (int m = 0; m < 4; ++m) {
;                 const f32x4 ca = acc[ai][bj][m][0], cb = acc[ai][bj][m][1];
;                 const int row = pm * 256 + ai * 128 + wr * 64 + m * 16 + fr;
;                 float o[4];
; #pragma unroll
;                 for (int e = 0; e < 4; ++e) {
;                     const float a1 = dppf<0x111>(ca[e]) + dppf<0x10F>(pa[e]), a2 = dppf<0x112>(ca[e]) + dppf<0x10E>(pa[e]);
;                     const float b1 = dppf<0x111>(cb[e]) + dppf<0x10F>(pb[e]), b2 = dppf<0x112>(cb[e]) + dppf<0x10E>(pb[e]);
;                     const float ya = fmaf(wa0[e], a2, fmaf(wa1[e], a1, fmaf(wa2[e], ca[e], ba[e])));
;                     const float yb = fmaf(wb0[e], b2, fmaf(wb1[e], b1, fmaf(wb2[e], cb[e], bb[e])));
;                     o[e] = silu_fast(ya) * yb; }
;                 if (m > 0 || fr >= 2) { u32x2 w; w.x = pk2(o[0], o[1]); w.y = pk2(o[2], o[3]); *(u32x2*)(E.d0 + (size_t)row * FFH + j0) = w; }
;                 if ((m == 0 && fr < 2) || (m == 3 && fr >= 14)) { float* hb = E.f0 + ((size_t)(row >> 6) * 4 + (m == 0 ? fr : fr - 12)) * FF2 + ncol; *(f32x4*)hb = ca; *(f32x4*)(hb + 4) = cb; }
;                 pa = ca; pb = cb;
	v_rcp_f32_e32 v168, v168
	v_rcp_f32_e32 v169, v169
	v_rcp_f32_e32 v170, v170
	v_rcp_f32_e32 v171, v171
	v_mov_b64_e32 v[174:175], v[224:225]
	v_mul_f32_e32 v160, v160, v168
	v_mul_f32_e32 v161, v161, v169
	v_mul_f32_e32 v162, v162, v170
	v_mul_f32_e32 v163, v163, v171
	v_mul_f32_e32 v160, v164, v160
	v_mul_f32_e32 v161, v165, v161
	v_mul_f32_e32 v162, v166, v162
	v_mul_f32_e32 v163, v167, v163
	v_cvt_pk_bf16_f32 v172, v160, v161
	v_cvt_pk_bf16_f32 v173, v162, v163
	s_and_saveexec_b64 s[76:77], s[38:39]
	global_store_dwordx2 v[174:175], v[172:173], off
	s_or_b64 exec, exec, s[76:77]
	s_ashr_i32 s80, s71, 6
	s_lshl_b32 s80, s80, 2
	s_add_i32 s80, s80, 8
	v_add_u32_e32 v226, s80, v188
	v_mov_b64_e32 v[174:175], s[8:9]
	s_movk_i32 s80, 0x5800
	v_mad_i64_i32 v[174:175], s[78:79], v226, s80, v[174:175]
	v_lshl_add_u64 v[174:175], v[228:229], 2, v[174:175]
	s_and_saveexec_b64 s[76:77], s[40:41]
	global_store_dwordx4 v[174:175], v[60:63], off
	global_store_dwordx4 v[174:175], v[56:59], off offset:16
	s_or_b64 exec, exec, s[76:77]
	v_fma_f32 v208, v152, v52, v156
	v_fma_f32 v209, v153, v53, v157
	v_fma_f32 v210, v154, v54, v158
	v_fma_f32 v211, v155, v55, v159
	v_fma_f32 v212, v144, v40, v148
	v_fma_f32 v213, v145, v41, v149
	v_fma_f32 v214, v146, v42, v150
	v_fma_f32 v215, v147, v43, v151
	v_fmac_f32_dpp v208, v52, v140 row_shr:1 row_mask:0xf bank_mask:0xf
	v_fmac_f32_dpp v209, v53, v141 row_shr:1 row_mask:0xf bank_mask:0xf
	v_fmac_f32_dpp v210, v54, v142 row_shr:1 row_mask:0xf bank_mask:0xf
	v_fmac_f32_dpp v211, v55, v143 row_shr:1 row_mask:0xf bank_mask:0xf
	v_fmac_f32_dpp v212, v40, v132 row_shr:1 row_mask:0xf bank_mask:0xf
	v_fmac_f32_dpp v213, v41, v133 row_shr:1 row_mask:0xf bank_mask:0xf
	v_fmac_f32_dpp v214, v42, v134 row_shr:1 row_mask:0xf bank_mask:0xf
	v_fmac_f32_dpp v215, v43, v135 row_shr:1 row_mask:0xf bank_mask:0xf
	v_fmac_f32_dpp v208, v60, v140 row_shl:15 row_mask:0xf bank_mask:0xf
	v_fmac_f32_dpp v209, v61, v141 row_shl:15 row_mask:0xf bank_mask:0xf
	v_fmac_f32_dpp v210, v62, v142 row_shl:15 row_mask:0xf bank_mask:0xf
	v_fmac_f32_dpp v211, v63, v143 row_shl:15 row_mask:0xf bank_mask:0xf
	v_fmac_f32_dpp v212, v56, v132 row_shl:15 row_mask:0xf bank_mask:0xf
	v_fmac_f32_dpp v213, v57, v133 row_shl:15 row_mask:0xf bank_mask:0xf
	v_fmac_f32_dpp v214, v58, v134 row_shl:15 row_mask:0xf bank_mask:0xf
	v_fmac_f32_dpp v215, v59, v135 row_shl:15 row_mask:0xf bank_mask:0xf
	v_fmac_f32_dpp v208, v52, v136 row_shr:2 row_mask:0xf bank_mask:0xf
	v_fmac_f32_dpp v209, v53, v137 row_shr:2 row_mask:0xf bank_mask:0xf
	v_fmac_f32_dpp v210, v54, v138 row_shr:2 row_mask:0xf bank_mask:0xf
	v_fmac_f32_dpp v211, v55, v139 row_shr:2 row_mask:0xf bank_mask:0xf
	v_fmac_f32_dpp v212, v40, v128 row_shr:2 row_mask:0xf bank_mask:0xf
	v_fmac_f32_dpp v213, v41, v129 row_shr:2 row_mask:0xf bank_mask:0xf
	v_fmac_f32_dpp v214, v42, v130 row_shr:2 row_mask:0xf bank_mask:0xf
	v_fmac_f32_dpp v215, v43, v131 row_shr:2 row_mask:0xf bank_mask:0xf
	v_fmac_f32_dpp v208, v60, v136 row_shl:14 row_mask:0xf bank_mask:0xf
	v_fmac_f32_dpp v209, v61, v137 row_shl:14 row_mask:0xf bank_mask:0xf
	v_fmac_f32_dpp v210, v62, v138 row_shl:14 row_mask:0xf bank_mask:0xf
	v_fmac_f32_dpp v211, v63, v139 row_shl:14 row_mask:0xf bank_mask:0xf
	v_fmac_f32_dpp v212, v56, v128 row_shl:14 row_mask:0xf bank_mask:0xf
	v_fmac_f32_dpp v213, v57, v129 row_shl:14 row_mask:0xf bank_mask:0xf
	v_fmac_f32_dpp v214, v58, v130 row_shl:14 row_mask:0xf bank_mask:0xf
	v_fmac_f32_dpp v215, v59, v131 row_shl:14 row_mask:0xf bank_mask:0xf
	v_mul_f32_e32 v216, 0xbfb8aa3b, v208
	v_mul_f32_e32 v217, 0xbfb8aa3b, v209
	v_mul_f32_e32 v218, 0xbfb8aa3b, v210
	v_mul_f32_e32 v219, 0xbfb8aa3b, v211
	v_exp_f32_e32 v216, v216
	v_exp_f32_e32 v217, v217
	v_exp_f32_e32 v218, v218
	v_exp_f32_e32 v219, v219
	v_add_f32_e32 v216, 1.0, v216
	v_add_f32_e32 v217, 1.0, v217
	v_add_f32_e32 v218, 1.0, v218
	v_add_f32_e32 v219, 1.0, v219
	v_rcp_f32_e32 v216, v216
	v_rcp_f32_e32 v217, v217
	v_rcp_f32_e32 v218, v218
	v_rcp_f32_e32 v219, v219
	s_mov_b32 s80, 0x16000
	s_mov_b32 s81, 0
	v_lshl_add_u64 v[222:223], v[224:225], 0, s[80:81]
	v_mul_f32_e32 v208, v208, v216
	v_mul_f32_e32 v209, v209, v217
	v_mul_f32_e32 v210, v210, v218
	v_mul_f32_e32 v211, v211, v219
	v_mul_f32_e32 v208, v212, v208
	v_mul_f32_e32 v209, v213, v209
	v_mul_f32_e32 v210, v214, v210
	v_mul_f32_e32 v211, v215, v211
	v_cvt_pk_bf16_f32 v220, v208, v209
	v_cvt_pk_bf16_f32 v221, v210, v211
	global_store_dwordx2 v[222:223], v[220:221], off
	v_fma_f32 v160, v152, v36, v156
	v_fma_f32 v161, v153, v37, v157
	v_fma_f32 v162, v154, v38, v158
	v_fma_f32 v163, v155, v39, v159
	v_fma_f32 v164, v144, v16, v148
	v_fma_f32 v165, v145, v17, v149
	v_fma_f32 v166, v146, v18, v150
	v_fma_f32 v167, v147, v19, v151
	v_fmac_f32_dpp v160, v36, v140 row_shr:1 row_mask:0xf bank_mask:0xf
	v_fmac_f32_dpp v161, v37, v141 row_shr:1 row_mask:0xf bank_mask:0xf
	v_fmac_f32_dpp v162, v38, v142 row_shr:1 row_mask:0xf bank_mask:0xf
	v_fmac_f32_dpp v163, v39, v143 row_shr:1 row_mask:0xf bank_mask:0xf
	v_fmac_f32_dpp v164, v16, v132 row_shr:1 row_mask:0xf bank_mask:0xf
	v_fmac_f32_dpp v165, v17, v133 row_shr:1 row_mask:0xf bank_mask:0xf
	v_fmac_f32_dpp v166, v18, v134 row_shr:1 row_mask:0xf bank_mask:0xf
	v_fmac_f32_dpp v167, v19, v135 row_shr:1 row_mask:0xf bank_mask:0xf
	v_fmac_f32_dpp v160, v52, v140 row_shl:15 row_mask:0xf bank_mask:0xf
	v_fmac_f32_dpp v161, v53, v141 row_shl:15 row_mask:0xf bank_mask:0xf
	v_fmac_f32_dpp v162, v54, v142 row_shl:15 row_mask:0xf bank_mask:0xf
	v_fmac_f32_dpp v163, v55, v143 row_shl:15 row_mask:0xf bank_mask:0xf
	v_fmac_f32_dpp v164, v40, v132 row_shl:15 row_mask:0xf bank_mask:0xf
; DI float silu_fast(float x) { return x * __builtin_amdgcn_rcpf(1.f + __expf(-x)); }
; template <int CTRL> DI float dppf(float v) { return __builtin_bit_cast(float, __builtin_amdgcn_update_dpp(0, __builtin_bit_cast(int, v), CTRL, 0xf, 0xf, true)); }
; DI void Epi::fused(const f32x4 (&acc)[2][2][4][2], int pm, int pn, int wr, int wc, int fr, int fq) const {
;     ...
;             for (int m = 0; m < 4; ++m) {
;                 const f32x4 ca = acc[ai][bj][m][0], cb = acc[ai][bj][m][1];
;                 const int row = pm * 256 + ai * 128 + wr * 64 + m * 16 + fr;
;                 float o[4];
; #pragma unroll
;                 for (int e = 0; e < 4; ++e) {
;                     const float a1 = dppf<0x111>(ca[e]) + dppf<0x10F>(pa[e]), a2 = dppf<0x112>(ca[e]) + dppf<0x10E>(pa[e]);
;                     const float b1 = dppf<0x111>(cb[e]) + dppf<0x10F>(pb[e]), b2 = dppf<0x112>(cb[e]) + dppf<0x10E>(pb[e]);
;                     const float ya = fmaf(wa0[e], a2, fmaf(wa1[e], a1, fmaf(wa2[e], ca[e], ba[e])));
;                     const float yb = fmaf(wb0[e], b2, fmaf(wb1[e], b1, fmaf(wb2[e], cb[e], bb[e])));
;                     o[e] = silu_fast(ya) * yb; }
;                 if (m > 0 || fr >= 2) { u32x2 w; w.x = pk2(o[0], o[1]); w.y = pk2(o[2], o[3]); *(u32x2*)(E.d0 + (size_t)row * FFH + j0) = w; }
;                 if ((m == 0 && fr < 2) || (m == 3 && fr >= 14)) { float* hb = E.f0 + ((size_t)(row >> 6) * 4 + (m == 0 ? fr : fr - 12)) * FF2 + ncol; *(f32x4*)hb = ca; *(f32x4*)(hb + 4) = cb; }
;                 pa = ca; pb = cb;
	v_fmac_f32_dpp v165, v41, v133 row_shl:15 row_mask:0xf bank_mask:0xf
	v_fmac_f32_dpp v166, v42, v134 row_shl:15 row_mask:0xf bank_mask:0xf
	v_fmac_f32_dpp v167, v43, v135 row_shl:15 row_mask:0xf bank_mask:0xf
	v_fmac_f32_dpp v160, v36, v136 row_shr:2 row_mask:0xf bank_mask:0xf
	v_fmac_f32_dpp v161, v37, v137 row_shr:2 row_mask:0xf bank_mask:0xf
	v_fmac_f32_dpp v162, v38, v138 row_shr:2 row_mask:0xf bank_mask:0xf
	v_fmac_f32_dpp v163, v39, v139 row_shr:2 row_mask:0xf bank_mask:0xf
	v_fmac_f32_dpp v164, v16, v128 row_shr:2 row_mask:0xf bank_mask:0xf
	v_fmac_f32_dpp v165, v17, v129 row_shr:2 row_mask:0xf bank_mask:0xf
	v_fmac_f32_dpp v166, v18, v130 row_shr:2 row_mask:0xf bank_mask:0xf
	v_fmac_f32_dpp v167, v19, v131 row_shr:2 row_mask:0xf bank_mask:0xf
	v_fmac_f32_dpp v160, v52, v136 row_shl:14 row_mask:0xf bank_mask:0xf
	v_fmac_f32_dpp v161, v53, v137 row_shl:14 row_mask:0xf bank_mask:0xf
	v_fmac_f32_dpp v162, v54, v138 row_shl:14 row_mask:0xf bank_mask:0xf
	v_fmac_f32_dpp v163, v55, v139 row_shl:14 row_mask:0xf bank_mask:0xf
	v_fmac_f32_dpp v164, v40, v128 row_shl:14 row_mask:0xf bank_mask:0xf
	v_fmac_f32_dpp v165, v41, v129 row_shl:14 row_mask:0xf bank_mask:0xf
	v_fmac_f32_dpp v166, v42, v130 row_shl:14 row_mask:0xf bank_mask:0xf
	v_fmac_f32_dpp v167, v43, v131 row_shl:14 row_mask:0xf bank_mask:0xf
	v_mul_f32_e32 v168, 0xbfb8aa3b, v160
	v_mul_f32_e32 v169, 0xbfb8aa3b, v161
	v_mul_f32_e32 v170, 0xbfb8aa3b, v162
	v_mul_f32_e32 v171, 0xbfb8aa3b, v163
	v_exp_f32_e32 v168, v168
	v_exp_f32_e32 v169, v169
	v_exp_f32_e32 v170, v170
	v_exp_f32_e32 v171, v171
	v_add_f32_e32 v168, 1.0, v168
	v_add_f32_e32 v169, 1.0, v169
	v_add_f32_e32 v170, 1.0, v170
	v_add_f32_e32 v171, 1.0, v171
	v_rcp_f32_e32 v168, v168
	v_rcp_f32_e32 v169, v169
	v_rcp_f32_e32 v170, v170
	v_rcp_f32_e32 v171, v171
	s_mov_b32 s80, 0x2c000
	s_mov_b32 s81, 0
	v_lshl_add_u64 v[174:175], v[224:225], 0, s[80:81]
	v_mul_f32_e32 v160, v160, v168
	v_mul_f32_e32 v161, v161, v169
	v_mul_f32_e32 v162, v162, v170
	v_mul_f32_e32 v163, v163, v171
	v_mul_f32_e32 v160, v164, v160
	v_mul_f32_e32 v161, v165, v161
	v_mul_f32_e32 v162, v166, v162
	v_mul_f32_e32 v163, v167, v163
	v_cvt_pk_bf16_f32 v172, v160, v161
	v_cvt_pk_bf16_f32 v173, v162, v163
	global_store_dwordx2 v[174:175], v[172:173], off
	v_fma_f32 v208, v152, v12, v156
	v_fma_f32 v209, v153, v13, v157
	v_fma_f32 v210, v154, v14, v158
	v_fma_f32 v211, v155, v15, v159
	v_fma_f32 v212, v144, v0, v148
	v_fma_f32 v213, v145, v1, v149
	v_fma_f32 v214, v146, v2, v150
	v_fma_f32 v215, v147, v3, v151
	v_fmac_f32_dpp v208, v12, v140 row_shr:1 row_mask:0xf bank_mask:0xf
	v_fmac_f32_dpp v209, v13, v141 row_shr:1 row_mask:0xf bank_mask:0xf
	v_fmac_f32_dpp v210, v14, v142 row_shr:1 row_mask:0xf bank_mask:0xf
	v_fmac_f32_dpp v211, v15, v143 row_shr:1 row_mask:0xf bank_mask:0xf
	v_fmac_f32_dpp v212, v0, v132 row_shr:1 row_mask:0xf bank_mask:0xf
	v_fmac_f32_dpp v213, v1, v133 row_shr:1 row_mask:0xf bank_mask:0xf
	v_fmac_f32_dpp v214, v2, v134 row_shr:1 row_mask:0xf bank_mask:0xf
	v_fmac_f32_dpp v215, v3, v135 row_shr:1 row_mask:0xf bank_mask:0xf
	v_fmac_f32_dpp v208, v36, v140 row_shl:15 row_mask:0xf bank_mask:0xf
	v_fmac_f32_dpp v209, v37, v141 row_shl:15 row_mask:0xf bank_mask:0xf
	v_fmac_f32_dpp v210, v38, v142 row_shl:15 row_mask:0xf bank_mask:0xf
	v_fmac_f32_dpp v211, v39, v143 row_shl:15 row_mask:0xf bank_mask:0xf
	v_fmac_f32_dpp v212, v16, v132 row_shl:15 row_mask:0xf bank_mask:0xf
	v_fmac_f32_dpp v213, v17, v133 row_shl:15 row_mask:0xf bank_mask:0xf
	v_fmac_f32_dpp v214, v18, v134 row_shl:15 row_mask:0xf bank_mask:0xf
	v_fmac_f32_dpp v215, v19, v135 row_shl:15 row_mask:0xf bank_mask:0xf
	v_fmac_f32_dpp v208, v12, v136 row_shr:2 row_mask:0xf bank_mask:0xf
	v_fmac_f32_dpp v209, v13, v137 row_shr:2 row_mask:0xf bank_mask:0xf
	v_fmac_f32_dpp v210, v14, v138 row_shr:2 row_mask:0xf bank_mask:0xf
	v_fmac_f32_dpp v211, v15, v139 row_shr:2 row_mask:0xf bank_mask:0xf
	v_fmac_f32_dpp v212, v0, v128 row_shr:2 row_mask:0xf bank_mask:0xf
	v_fmac_f32_dpp v213, v1, v129 row_shr:2 row_mask:0xf bank_mask:0xf
	v_fmac_f32_dpp v214, v2, v130 row_shr:2 row_mask:0xf bank_mask:0xf
	v_fmac_f32_dpp v215, v3, v131 row_shr:2 row_mask:0xf bank_mask:0xf
	v_fmac_f32_dpp v208, v36, v136 row_shl:14 row_mask:0xf bank_mask:0xf
	v_fmac_f32_dpp v209, v37, v137 row_shl:14 row_mask:0xf bank_mask:0xf
	v_fmac_f32_dpp v210, v38, v138 row_shl:14 row_mask:0xf bank_mask:0xf
	v_fmac_f32_dpp v211, v39, v139 row_shl:14 row_mask:0xf bank_mask:0xf
	v_fmac_f32_dpp v212, v16, v128 row_shl:14 row_mask:0xf bank_mask:0xf
	v_fmac_f32_dpp v213, v17, v129 row_shl:14 row_mask:0xf bank_mask:0xf
	v_fmac_f32_dpp v214, v18, v130 row_shl:14 row_mask:0xf bank_mask:0xf
	v_fmac_f32_dpp v215, v19, v131 row_shl:14 row_mask:0xf bank_mask:0xf
	v_mul_f32_e32 v216, 0xbfb8aa3b, v208
	v_mul_f32_e32 v217, 0xbfb8aa3b, v209
	v_mul_f32_e32 v218, 0xbfb8aa3b, v210
	v_mul_f32_e32 v219, 0xbfb8aa3b, v211
	v_exp_f32_e32 v216, v216
	v_exp_f32_e32 v217, v217
	v_exp_f32_e32 v218, v218
	v_exp_f32_e32 v219, v219
	v_add_f32_e32 v216, 1.0, v216
	v_add_f32_e32 v217, 1.0, v217
	v_add_f32_e32 v218, 1.0, v218
	v_add_f32_e32 v219, 1.0, v219
	v_rcp_f32_e32 v216, v216
	v_rcp_f32_e32 v217, v217
	v_rcp_f32_e32 v218, v218
	v_rcp_f32_e32 v219, v219
	s_mov_b32 s80, 0x42000
	s_mov_b32 s81, 0
	v_lshl_add_u64 v[222:223], v[224:225], 0, s[80:81]
	v_mul_f32_e32 v208, v208, v216
	v_mul_f32_e32 v209, v209, v217
	v_mul_f32_e32 v210, v210, v218
	v_mul_f32_e32 v211, v211, v219
	v_mul_f32_e32 v208, v212, v208
	v_mul_f32_e32 v209, v213, v209
	v_mul_f32_e32 v210, v214, v210
	v_mul_f32_e32 v211, v215, v211
	v_cvt_pk_bf16_f32 v220, v208, v209
	v_cvt_pk_bf16_f32 v221, v210, v211
	global_store_dwordx2 v[222:223], v[220:221], off
	s_ashr_i32 s80, s71, 6
	s_lshl_b32 s80, s80, 2
	s_add_i32 s80, s80, 8
	v_add_u32_e32 v226, s80, v190
	v_mov_b64_e32 v[222:223], s[8:9]
	s_movk_i32 s80, 0x5800
	v_mad_i64_i32 v[222:223], s[78:79], v226, s80, v[222:223]
	v_lshl_add_u64 v[222:223], v[228:229], 2, v[222:223]
	s_and_saveexec_b64 s[76:77], s[42:43]
	global_store_dwordx4 v[222:223], v[12:15], off
	global_store_dwordx4 v[222:223], v[0:3], off offset:16
	s_or_b64 exec, exec, s[76:77]
	v_mov_b32_e32 v228, v199
	v_mov_b64_e32 v[224:225], s[12:13]
	s_movk_i32 s80, 0x1600
	v_mad_i64_i32 v[224:225], s[78:79], v228, s80, v[224:225]
	v_add_u32_e32 v228, 128, v240
	v_mov_b32_e32 v229, 0
	v_lshl_add_u64 v[224:225], v[228:229], 0, v[224:225]
	s_waitcnt vmcnt(8)
; DI float silu_fast(float x) { return x * __builtin_amdgcn_rcpf(1.f + __expf(-x)); }
; template <int CTRL> DI float dppf(float v) { return __builtin_bit_cast(float, __builtin_amdgcn_update_dpp(0, __builtin_bit_cast(int, v), CTRL, 0xf, 0xf, true)); }
; DI void Epi::fused(const f32x4 (&acc)[2][2][4][2], int pm, int pn, int wr, int wc, int fr, int fq) const {
;     ...
;             for (int m = 0; m < 4; ++m) {
;                 const f32x4 ca = acc[ai][bj][m][0], cb = acc[ai][bj][m][1];
;                 const int row = pm * 256 + ai * 128 + wr * 64 + m * 16 + fr;
;                 float o[4];
; #pragma unroll
;                 for (int e = 0; e < 4; ++e) {
;                     const float a1 = dppf<0x111>(ca[e]) + dppf<0x10F>(pa[e]), a2 = dppf<0x112>(ca[e]) + dppf<0x10E>(pa[e]);
;                     const float b1 = dppf<0x111>(cb[e]) + dppf<0x10F>(pb[e]), b2 = dppf<0x112>(cb[e]) + dppf<0x10E>(pb[e]);
;                     const float ya = fmaf(wa0[e], a2, fmaf(wa1[e], a1, fmaf(wa2[e], ca[e], ba[e])));
;                     const float yb = fmaf(wb0[e], b2, fmaf(wb1[e], b1, fmaf(wb2[e], cb[e], bb[e])));
;                     o[e] = silu_fast(ya) * yb; }
;                 if (m > 0 || fr >= 2) { u32x2 w; w.x = pk2(o[0], o[1]); w.y = pk2(o[2], o[3]); *(u32x2*)(E.d0 + (size_t)row * FFH + j0) = w; }
;                 if ((m == 0 && fr < 2) || (m == 3 && fr >= 14)) { float* hb = E.f0 + ((size_t)(row >> 6) * 4 + (m == 0 ? fr : fr - 12)) * FF2 + ncol; *(f32x4*)hb = ca; *(f32x4*)(hb + 4) = cb; }
;                 pa = ca; pb = cb;
	v_fma_f32 v160, v100, v112, v124
	v_fma_f32 v161, v101, v113, v125
	v_fma_f32 v162, v102, v114, v126
	v_fma_f32 v163, v103, v115, v127
	v_fma_f32 v164, v120, v108, v72
	v_fma_f32 v165, v121, v109, v73
	v_fma_f32 v166, v122, v110, v74
	v_fma_f32 v167, v123, v111, v75
	v_fmac_f32_dpp v160, v112, v88 row_shr:1 row_mask:0xf bank_mask:0xf
	v_fmac_f32_dpp v161, v113, v89 row_shr:1 row_mask:0xf bank_mask:0xf
	v_fmac_f32_dpp v162, v114, v90 row_shr:1 row_mask:0xf bank_mask:0xf
	v_fmac_f32_dpp v163, v115, v91 row_shr:1 row_mask:0xf bank_mask:0xf
	v_fmac_f32_dpp v164, v108, v116 row_shr:1 row_mask:0xf bank_mask:0xf
	v_fmac_f32_dpp v165, v109, v117 row_shr:1 row_mask:0xf bank_mask:0xf
	v_fmac_f32_dpp v166, v110, v118 row_shr:1 row_mask:0xf bank_mask:0xf
	v_fmac_f32_dpp v167, v111, v119 row_shr:1 row_mask:0xf bank_mask:0xf
	v_fmac_f32_dpp v160, v112, v84 row_shr:2 row_mask:0xf bank_mask:0xf
	v_fmac_f32_dpp v161, v113, v85 row_shr:2 row_mask:0xf bank_mask:0xf
	v_fmac_f32_dpp v162, v114, v86 row_shr:2 row_mask:0xf bank_mask:0xf
	v_fmac_f32_dpp v163, v115, v87 row_shr:2 row_mask:0xf bank_mask:0xf
	v_fmac_f32_dpp v164, v108, v104 row_shr:2 row_mask:0xf bank_mask:0xf
	v_fmac_f32_dpp v165, v109, v105 row_shr:2 row_mask:0xf bank_mask:0xf
	v_fmac_f32_dpp v166, v110, v106 row_shr:2 row_mask:0xf bank_mask:0xf
	v_fmac_f32_dpp v167, v111, v107 row_shr:2 row_mask:0xf bank_mask:0xf
	v_mul_f32_e32 v168, 0xbfb8aa3b, v160
	v_mul_f32_e32 v169, 0xbfb8aa3b, v161
	v_mul_f32_e32 v170, 0xbfb8aa3b, v162
	v_mul_f32_e32 v171, 0xbfb8aa3b, v163
	v_exp_f32_e32 v168, v168
	v_exp_f32_e32 v169, v169
	v_exp_f32_e32 v170, v170
	v_exp_f32_e32 v171, v171
	v_add_f32_e32 v168, 1.0, v168
	v_add_f32_e32 v169, 1.0, v169
	v_add_f32_e32 v170, 1.0, v170
	v_add_f32_e32 v171, 1.0, v171
	v_rcp_f32_e32 v168, v168
	v_rcp_f32_e32 v169, v169
	v_rcp_f32_e32 v170, v170
	v_rcp_f32_e32 v171, v171
	v_mov_b64_e32 v[174:175], v[224:225]
	v_mul_f32_e32 v160, v160, v168
	v_mul_f32_e32 v161, v161, v169
	v_mul_f32_e32 v162, v162, v170
	v_mul_f32_e32 v163, v163, v171
	v_mul_f32_e32 v160, v164, v160
	v_mul_f32_e32 v161, v165, v161
	v_mul_f32_e32 v162, v166, v162
	v_mul_f32_e32 v163, v167, v163
	v_cvt_pk_bf16_f32 v172, v160, v161
	v_cvt_pk_bf16_f32 v173, v162, v163
	s_and_saveexec_b64 s[76:77], s[38:39]
	global_store_dwordx2 v[174:175], v[172:173], off
	s_or_b64 exec, exec, s[76:77]
	s_ashr_i32 s80, s71, 6
	s_lshl_b32 s80, s80, 2
	v_add_u32_e32 v226, s80, v188
	v_mov_b64_e32 v[174:175], s[8:9]
	s_movk_i32 s80, 0x5800
	v_mad_i64_i32 v[174:175], s[78:79], v226, s80, v[174:175]
	v_lshl_add_u64 v[174:175], v[228:229], 2, v[174:175]
	s_and_saveexec_b64 s[76:77], s[40:41]
	global_store_dwordx4 v[174:175], v[112:115], off
	global_store_dwordx4 v[174:175], v[108:111], off offset:16
	s_or_b64 exec, exec, s[76:77]
	v_fma_f32 v208, v100, v96, v124
	v_fma_f32 v209, v101, v97, v125
	v_fma_f32 v210, v102, v98, v126
	v_fma_f32 v211, v103, v99, v127
	v_fma_f32 v212, v120, v92, v72
	v_fma_f32 v213, v121, v93, v73
	v_fma_f32 v214, v122, v94, v74
	v_fma_f32 v215, v123, v95, v75
	v_fmac_f32_dpp v208, v96, v88 row_shr:1 row_mask:0xf bank_mask:0xf
	v_fmac_f32_dpp v209, v97, v89 row_shr:1 row_mask:0xf bank_mask:0xf
	v_fmac_f32_dpp v210, v98, v90 row_shr:1 row_mask:0xf bank_mask:0xf
	v_fmac_f32_dpp v211, v99, v91 row_shr:1 row_mask:0xf bank_mask:0xf
	v_fmac_f32_dpp v212, v92, v116 row_shr:1 row_mask:0xf bank_mask:0xf
	v_fmac_f32_dpp v213, v93, v117 row_shr:1 row_mask:0xf bank_mask:0xf
	v_fmac_f32_dpp v214, v94, v118 row_shr:1 row_mask:0xf bank_mask:0xf
	v_fmac_f32_dpp v215, v95, v119 row_shr:1 row_mask:0xf bank_mask:0xf
	v_fmac_f32_dpp v208, v112, v88 row_shl:15 row_mask:0xf bank_mask:0xf
	v_fmac_f32_dpp v209, v113, v89 row_shl:15 row_mask:0xf bank_mask:0xf
	v_fmac_f32_dpp v210, v114, v90 row_shl:15 row_mask:0xf bank_mask:0xf
	v_fmac_f32_dpp v211, v115, v91 row_shl:15 row_mask:0xf bank_mask:0xf
	v_fmac_f32_dpp v212, v108, v116 row_shl:15 row_mask:0xf bank_mask:0xf
	v_fmac_f32_dpp v213, v109, v117 row_shl:15 row_mask:0xf bank_mask:0xf
	v_fmac_f32_dpp v214, v110, v118 row_shl:15 row_mask:0xf bank_mask:0xf
	v_fmac_f32_dpp v215, v111, v119 row_shl:15 row_mask:0xf bank_mask:0xf
	v_fmac_f32_dpp v208, v96, v84 row_shr:2 row_mask:0xf bank_mask:0xf
	v_fmac_f32_dpp v209, v97, v85 row_shr:2 row_mask:0xf bank_mask:0xf
	v_fmac_f32_dpp v210, v98, v86 row_shr:2 row_mask:0xf bank_mask:0xf
	v_fmac_f32_dpp v211, v99, v87 row_shr:2 row_mask:0xf bank_mask:0xf
	v_fmac_f32_dpp v212, v92, v104 row_shr:2 row_mask:0xf bank_mask:0xf
	v_fmac_f32_dpp v213, v93, v105 row_shr:2 row_mask:0xf bank_mask:0xf
	v_fmac_f32_dpp v214, v94, v106 row_shr:2 row_mask:0xf bank_mask:0xf
	v_fmac_f32_dpp v215, v95, v107 row_shr:2 row_mask:0xf bank_mask:0xf
	v_fmac_f32_dpp v208, v112, v84 row_shl:14 row_mask:0xf bank_mask:0xf
	v_fmac_f32_dpp v209, v113, v85 row_shl:14 row_mask:0xf bank_mask:0xf
	v_fmac_f32_dpp v210, v114, v86 row_shl:14 row_mask:0xf bank_mask:0xf
	v_fmac_f32_dpp v211, v115, v87 row_shl:14 row_mask:0xf bank_mask:0xf
	v_fmac_f32_dpp v212, v108, v104 row_shl:14 row_mask:0xf bank_mask:0xf
	v_fmac_f32_dpp v213, v109, v105 row_shl:14 row_mask:0xf bank_mask:0xf
	v_fmac_f32_dpp v214, v110, v106 row_shl:14 row_mask:0xf bank_mask:0xf
	v_fmac_f32_dpp v215, v111, v107 row_shl:14 row_mask:0xf bank_mask:0xf
	v_mul_f32_e32 v216, 0xbfb8aa3b, v208
	v_mul_f32_e32 v217, 0xbfb8aa3b, v209
	v_mul_f32_e32 v218, 0xbfb8aa3b, v210
	v_mul_f32_e32 v219, 0xbfb8aa3b, v211
	v_exp_f32_e32 v216, v216
	v_exp_f32_e32 v217, v217
	v_exp_f32_e32 v218, v218
	v_exp_f32_e32 v219, v219
	v_add_f32_e32 v216, 1.0, v216
	v_add_f32_e32 v217, 1.0, v217
	v_add_f32_e32 v218, 1.0, v218
	v_add_f32_e32 v219, 1.0, v219
; DI float silu_fast(float x) { return x * __builtin_amdgcn_rcpf(1.f + __expf(-x)); }
; template <int CTRL> DI float dppf(float v) { return __builtin_bit_cast(float, __builtin_amdgcn_update_dpp(0, __builtin_bit_cast(int, v), CTRL, 0xf, 0xf, true)); }
; DI void Epi::fused(const f32x4 (&acc)[2][2][4][2], int pm, int pn, int wr, int wc, int fr, int fq) const {
;     ...
;             for (int m = 0; m < 4; ++m) {
;                 const f32x4 ca = acc[ai][bj][m][0], cb = acc[ai][bj][m][1];
;                 const int row = pm * 256 + ai * 128 + wr * 64 + m * 16 + fr;
;                 float o[4];
; #pragma unroll
;                 for (int e = 0; e < 4; ++e) {
;                     const float a1 = dppf<0x111>(ca[e]) + dppf<0x10F>(pa[e]), a2 = dppf<0x112>(ca[e]) + dppf<0x10E>(pa[e]);
;                     const float b1 = dppf<0x111>(cb[e]) + dppf<0x10F>(pb[e]), b2 = dppf<0x112>(cb[e]) + dppf<0x10E>(pb[e]);
;                     const float ya = fmaf(wa0[e], a2, fmaf(wa1[e], a1, fmaf(wa2[e], ca[e], ba[e])));
;                     const float yb = fmaf(wb0[e], b2, fmaf(wb1[e], b1, fmaf(wb2[e], cb[e], bb[e])));
;                     o[e] = silu_fast(ya) * yb; }
;                 if (m > 0 || fr >= 2) { u32x2 w; w.x = pk2(o[0], o[1]); w.y = pk2(o[2], o[3]); *(u32x2*)(E.d0 + (size_t)row * FFH + j0) = w; }
;                 if ((m == 0 && fr < 2) || (m == 3 && fr >= 14)) { float* hb = E.f0 + ((size_t)(row >> 6) * 4 + (m == 0 ? fr : fr - 12)) * FF2 + ncol; *(f32x4*)hb = ca; *(f32x4*)(hb + 4) = cb; }
;                 pa = ca; pb = cb;
	v_rcp_f32_e32 v216, v216
	v_rcp_f32_e32 v217, v217
	v_rcp_f32_e32 v218, v218
	v_rcp_f32_e32 v219, v219
	s_mov_b32 s80, 0x16000
	s_mov_b32 s81, 0
	v_lshl_add_u64 v[222:223], v[224:225], 0, s[80:81]
	v_mul_f32_e32 v208, v208, v216
	v_mul_f32_e32 v209, v209, v217
	v_mul_f32_e32 v210, v210, v218
	v_mul_f32_e32 v211, v211, v219
	v_mul_f32_e32 v208, v212, v208
	v_mul_f32_e32 v209, v213, v209
	v_mul_f32_e32 v210, v214, v210
	v_mul_f32_e32 v211, v215, v211
	v_cvt_pk_bf16_f32 v220, v208, v209
	v_cvt_pk_bf16_f32 v221, v210, v211
	global_store_dwordx2 v[222:223], v[220:221], off
	v_fma_f32 v160, v100, v80, v124
	v_fma_f32 v161, v101, v81, v125
	v_fma_f32 v162, v102, v82, v126
	v_fma_f32 v163, v103, v83, v127
	v_fma_f32 v164, v120, v76, v72
	v_fma_f32 v165, v121, v77, v73
	v_fma_f32 v166, v122, v78, v74
	v_fma_f32 v167, v123, v79, v75
	v_fmac_f32_dpp v160, v80, v88 row_shr:1 row_mask:0xf bank_mask:0xf
	v_fmac_f32_dpp v161, v81, v89 row_shr:1 row_mask:0xf bank_mask:0xf
	v_fmac_f32_dpp v162, v82, v90 row_shr:1 row_mask:0xf bank_mask:0xf
	v_fmac_f32_dpp v163, v83, v91 row_shr:1 row_mask:0xf bank_mask:0xf
	v_fmac_f32_dpp v164, v76, v116 row_shr:1 row_mask:0xf bank_mask:0xf
	v_fmac_f32_dpp v165, v77, v117 row_shr:1 row_mask:0xf bank_mask:0xf
	v_fmac_f32_dpp v166, v78, v118 row_shr:1 row_mask:0xf bank_mask:0xf
	v_fmac_f32_dpp v167, v79, v119 row_shr:1 row_mask:0xf bank_mask:0xf
	v_fmac_f32_dpp v160, v96, v88 row_shl:15 row_mask:0xf bank_mask:0xf
	v_fmac_f32_dpp v161, v97, v89 row_shl:15 row_mask:0xf bank_mask:0xf
	v_fmac_f32_dpp v162, v98, v90 row_shl:15 row_mask:0xf bank_mask:0xf
	v_fmac_f32_dpp v163, v99, v91 row_shl:15 row_mask:0xf bank_mask:0xf
	v_fmac_f32_dpp v164, v92, v116 row_shl:15 row_mask:0xf bank_mask:0xf
	v_fmac_f32_dpp v165, v93, v117 row_shl:15 row_mask:0xf bank_mask:0xf
	v_fmac_f32_dpp v166, v94, v118 row_shl:15 row_mask:0xf bank_mask:0xf
	v_fmac_f32_dpp v167, v95, v119 row_shl:15 row_mask:0xf bank_mask:0xf
	v_fmac_f32_dpp v160, v80, v84 row_shr:2 row_mask:0xf bank_mask:0xf
	v_fmac_f32_dpp v161, v81, v85 row_shr:2 row_mask:0xf bank_mask:0xf
	v_fmac_f32_dpp v162, v82, v86 row_shr:2 row_mask:0xf bank_mask:0xf
	v_fmac_f32_dpp v163, v83, v87 row_shr:2 row_mask:0xf bank_mask:0xf
	v_fmac_f32_dpp v164, v76, v104 row_shr:2 row_mask:0xf bank_mask:0xf
	v_fmac_f32_dpp v165, v77, v105 row_shr:2 row_mask:0xf bank_mask:0xf
	v_fmac_f32_dpp v166, v78, v106 row_shr:2 row_mask:0xf bank_mask:0xf
	v_fmac_f32_dpp v167, v79, v107 row_shr:2 row_mask:0xf bank_mask:0xf
	v_fmac_f32_dpp v160, v96, v84 row_shl:14 row_mask:0xf bank_mask:0xf
	v_fmac_f32_dpp v161, v97, v85 row_shl:14 row_mask:0xf bank_mask:0xf
	v_fmac_f32_dpp v162, v98, v86 row_shl:14 row_mask:0xf bank_mask:0xf
	v_fmac_f32_dpp v163, v99, v87 row_shl:14 row_mask:0xf bank_mask:0xf
	v_fmac_f32_dpp v164, v92, v104 row_shl:14 row_mask:0xf bank_mask:0xf
	v_fmac_f32_dpp v165, v93, v105 row_shl:14 row_mask:0xf bank_mask:0xf
	v_fmac_f32_dpp v166, v94, v106 row_shl:14 row_mask:0xf bank_mask:0xf
	v_fmac_f32_dpp v167, v95, v107 row_shl:14 row_mask:0xf bank_mask:0xf
	v_mul_f32_e32 v168, 0xbfb8aa3b, v160
	v_mul_f32_e32 v169, 0xbfb8aa3b, v161
	v_mul_f32_e32 v170, 0xbfb8aa3b, v162
	v_mul_f32_e32 v171, 0xbfb8aa3b, v163
	v_exp_f32_e32 v168, v168
	v_exp_f32_e32 v169, v169
	v_exp_f32_e32 v170, v170
	v_exp_f32_e32 v171, v171
	v_add_f32_e32 v168, 1.0, v168
	v_add_f32_e32 v169, 1.0, v169
	v_add_f32_e32 v170, 1.0, v170
	v_add_f32_e32 v171, 1.0, v171
	v_rcp_f32_e32 v168, v168
	v_rcp_f32_e32 v169, v169
	v_rcp_f32_e32 v170, v170
	v_rcp_f32_e32 v171, v171
	s_mov_b32 s80, 0x2c000
	s_mov_b32 s81, 0
	v_lshl_add_u64 v[174:175], v[224:225], 0, s[80:81]
	v_mul_f32_e32 v160, v160, v168
	v_mul_f32_e32 v161, v161, v169
	v_mul_f32_e32 v162, v162, v170
	v_mul_f32_e32 v163, v163, v171
	v_mul_f32_e32 v160, v164, v160
	v_mul_f32_e32 v161, v165, v161
	v_mul_f32_e32 v162, v166, v162
	v_mul_f32_e32 v163, v167, v163
	v_cvt_pk_bf16_f32 v172, v160, v161
	v_cvt_pk_bf16_f32 v173, v162, v163
	global_store_dwordx2 v[174:175], v[172:173], off
	v_fma_f32 v208, v100, v68, v124
	v_fma_f32 v209, v101, v69, v125
	v_fma_f32 v210, v102, v70, v126
	v_fma_f32 v211, v103, v71, v127
	v_fma_f32 v212, v120, v64, v72
	v_fma_f32 v213, v121, v65, v73
	v_fma_f32 v214, v122, v66, v74
	v_fma_f32 v215, v123, v67, v75
	v_fmac_f32_dpp v208, v68, v88 row_shr:1 row_mask:0xf bank_mask:0xf
	v_fmac_f32_dpp v209, v69, v89 row_shr:1 row_mask:0xf bank_mask:0xf
	v_fmac_f32_dpp v210, v70, v90 row_shr:1 row_mask:0xf bank_mask:0xf
	v_fmac_f32_dpp v211, v71, v91 row_shr:1 row_mask:0xf bank_mask:0xf
	v_fmac_f32_dpp v212, v64, v116 row_shr:1 row_mask:0xf bank_mask:0xf
	v_fmac_f32_dpp v213, v65, v117 row_shr:1 row_mask:0xf bank_mask:0xf
	v_fmac_f32_dpp v214, v66, v118 row_shr:1 row_mask:0xf bank_mask:0xf
	v_fmac_f32_dpp v215, v67, v119 row_shr:1 row_mask:0xf bank_mask:0xf
	v_fmac_f32_dpp v208, v80, v88 row_shl:15 row_mask:0xf bank_mask:0xf
	v_fmac_f32_dpp v209, v81, v89 row_shl:15 row_mask:0xf bank_mask:0xf
	v_fmac_f32_dpp v210, v82, v90 row_shl:15 row_mask:0xf bank_mask:0xf
	v_fmac_f32_dpp v211, v83, v91 row_shl:15 row_mask:0xf bank_mask:0xf
	v_fmac_f32_dpp v212, v76, v116 row_shl:15 row_mask:0xf bank_mask:0xf
	v_fmac_f32_dpp v213, v77, v117 row_shl:15 row_mask:0xf bank_mask:0xf
	v_fmac_f32_dpp v214, v78, v118 row_shl:15 row_mask:0xf bank_mask:0xf
	v_fmac_f32_dpp v215, v79, v119 row_shl:15 row_mask:0xf bank_mask:0xf
	v_fmac_f32_dpp v208, v68, v84 row_shr:2 row_mask:0xf bank_mask:0xf
	v_fmac_f32_dpp v209, v69, v85 row_shr:2 row_mask:0xf bank_mask:0xf
	v_fmac_f32_dpp v210, v70, v86 row_shr:2 row_mask:0xf bank_mask:0xf
	v_fmac_f32_dpp v211, v71, v87 row_shr:2 row_mask:0xf bank_mask:0xf
; DI float silu_fast(float x) { return x * __builtin_amdgcn_rcpf(1.f + __expf(-x)); }
; template <int CTRL> DI float dppf(float v) { return __builtin_bit_cast(float, __builtin_amdgcn_update_dpp(0, __builtin_bit_cast(int, v), CTRL, 0xf, 0xf, true)); }
; DI void Epi::fused(const f32x4 (&acc)[2][2][4][2], int pm, int pn, int wr, int wc, int fr, int fq) const {
;     ...
;             for (int m = 0; m < 4; ++m) {
;                 const f32x4 ca = acc[ai][bj][m][0], cb = acc[ai][bj][m][1];
;                 const int row = pm * 256 + ai * 128 + wr * 64 + m * 16 + fr;
;                 float o[4];
; #pragma unroll
;                 for (int e = 0; e < 4; ++e) {
;                     const float a1 = dppf<0x111>(ca[e]) + dppf<0x10F>(pa[e]), a2 = dppf<0x112>(ca[e]) + dppf<0x10E>(pa[e]);
;                     const float b1 = dppf<0x111>(cb[e]) + dppf<0x10F>(pb[e]), b2 = dppf<0x112>(cb[e]) + dppf<0x10E>(pb[e]);
;                     const float ya = fmaf(wa0[e], a2, fmaf(wa1[e], a1, fmaf(wa2[e], ca[e], ba[e])));
;                     const float yb = fmaf(wb0[e], b2, fmaf(wb1[e], b1, fmaf(wb2[e], cb[e], bb[e])));
;                     o[e] = silu_fast(ya) * yb; }
;                 if (m > 0 || fr >= 2) { u32x2 w; w.x = pk2(o[0], o[1]); w.y = pk2(o[2], o[3]); *(u32x2*)(E.d0 + (size_t)row * FFH + j0) = w; }
;                 if ((m == 0 && fr < 2) || (m == 3 && fr >= 14)) { float* hb = E.f0 + ((size_t)(row >> 6) * 4 + (m == 0 ? fr : fr - 12)) * FF2 + ncol; *(f32x4*)hb = ca; *(f32x4*)(hb + 4) = cb; }
;                 pa = ca; pb = cb;
	v_fmac_f32_dpp v212, v64, v104 row_shr:2 row_mask:0xf bank_mask:0xf
	v_fmac_f32_dpp v213, v65, v105 row_shr:2 row_mask:0xf bank_mask:0xf
	v_fmac_f32_dpp v214, v66, v106 row_shr:2 row_mask:0xf bank_mask:0xf
	v_fmac_f32_dpp v215, v67, v107 row_shr:2 row_mask:0xf bank_mask:0xf
	v_fmac_f32_dpp v208, v80, v84 row_shl:14 row_mask:0xf bank_mask:0xf
	v_fmac_f32_dpp v209, v81, v85 row_shl:14 row_mask:0xf bank_mask:0xf
	v_fmac_f32_dpp v210, v82, v86 row_shl:14 row_mask:0xf bank_mask:0xf
	v_fmac_f32_dpp v211, v83, v87 row_shl:14 row_mask:0xf bank_mask:0xf
	v_fmac_f32_dpp v212, v76, v104 row_shl:14 row_mask:0xf bank_mask:0xf
	v_fmac_f32_dpp v213, v77, v105 row_shl:14 row_mask:0xf bank_mask:0xf
	v_fmac_f32_dpp v214, v78, v106 row_shl:14 row_mask:0xf bank_mask:0xf
	v_fmac_f32_dpp v215, v79, v107 row_shl:14 row_mask:0xf bank_mask:0xf
	v_mul_f32_e32 v216, 0xbfb8aa3b, v208
	v_mul_f32_e32 v217, 0xbfb8aa3b, v209
	v_mul_f32_e32 v218, 0xbfb8aa3b, v210
	v_mul_f32_e32 v219, 0xbfb8aa3b, v211
	v_exp_f32_e32 v216, v216
	v_exp_f32_e32 v217, v217
	v_exp_f32_e32 v218, v218
	v_exp_f32_e32 v219, v219
	v_add_f32_e32 v216, 1.0, v216
	v_add_f32_e32 v217, 1.0, v217
	v_add_f32_e32 v218, 1.0, v218
	v_add_f32_e32 v219, 1.0, v219
	v_rcp_f32_e32 v216, v216
	v_rcp_f32_e32 v217, v217
	v_rcp_f32_e32 v218, v218
	v_rcp_f32_e32 v219, v219
	s_mov_b32 s80, 0x42000
	s_mov_b32 s81, 0
	v_lshl_add_u64 v[222:223], v[224:225], 0, s[80:81]
	v_mul_f32_e32 v208, v208, v216
	v_mul_f32_e32 v209, v209, v217
	v_mul_f32_e32 v210, v210, v218
	v_mul_f32_e32 v211, v211, v219
	v_mul_f32_e32 v208, v212, v208
	v_mul_f32_e32 v209, v213, v209
	v_mul_f32_e32 v210, v214, v210
	v_mul_f32_e32 v211, v215, v211
	v_cvt_pk_bf16_f32 v220, v208, v209
	v_cvt_pk_bf16_f32 v221, v210, v211
	global_store_dwordx2 v[222:223], v[220:221], off
	s_ashr_i32 s80, s71, 6
	s_lshl_b32 s80, s80, 2
	v_add_u32_e32 v226, s80, v190
	v_mov_b64_e32 v[222:223], s[8:9]
	s_movk_i32 s80, 0x5800
	v_mad_i64_i32 v[222:223], s[78:79], v226, s80, v[222:223]
	v_lshl_add_u64 v[222:223], v[228:229], 2, v[222:223]
	s_and_saveexec_b64 s[76:77], s[42:43]
	global_store_dwordx4 v[222:223], v[68:71], off
	global_store_dwordx4 v[222:223], v[64:67], off offset:16
	s_or_b64 exec, exec, s[76:77]
	v_add_u32_e32 v228, 128, v199
	v_mov_b64_e32 v[224:225], s[12:13]
	s_movk_i32 s80, 0x1600
	v_mad_i64_i32 v[224:225], s[78:79], v228, s80, v[224:225]
	v_add_u32_e32 v228, 128, v240
	v_mov_b32_e32 v229, 0
	v_lshl_add_u64 v[224:225], v[228:229], 0, v[224:225]
	v_fma_f32 v160, v100, v48, v124
	v_fma_f32 v161, v101, v49, v125
	v_fma_f32 v162, v102, v50, v126
	v_fma_f32 v163, v103, v51, v127
	v_fma_f32 v164, v120, v44, v72
	v_fma_f32 v165, v121, v45, v73
	v_fma_f32 v166, v122, v46, v74
	v_fma_f32 v167, v123, v47, v75
	v_fmac_f32_dpp v160, v48, v88 row_shr:1 row_mask:0xf bank_mask:0xf
	v_fmac_f32_dpp v161, v49, v89 row_shr:1 row_mask:0xf bank_mask:0xf
	v_fmac_f32_dpp v162, v50, v90 row_shr:1 row_mask:0xf bank_mask:0xf
	v_fmac_f32_dpp v163, v51, v91 row_shr:1 row_mask:0xf bank_mask:0xf
	v_fmac_f32_dpp v164, v44, v116 row_shr:1 row_mask:0xf bank_mask:0xf
	v_fmac_f32_dpp v165, v45, v117 row_shr:1 row_mask:0xf bank_mask:0xf
	v_fmac_f32_dpp v166, v46, v118 row_shr:1 row_mask:0xf bank_mask:0xf
	v_fmac_f32_dpp v167, v47, v119 row_shr:1 row_mask:0xf bank_mask:0xf
	v_fmac_f32_dpp v160, v48, v84 row_shr:2 row_mask:0xf bank_mask:0xf
	v_fmac_f32_dpp v161, v49, v85 row_shr:2 row_mask:0xf bank_mask:0xf
	v_fmac_f32_dpp v162, v50, v86 row_shr:2 row_mask:0xf bank_mask:0xf
	v_fmac_f32_dpp v163, v51, v87 row_shr:2 row_mask:0xf bank_mask:0xf
	v_fmac_f32_dpp v164, v44, v104 row_shr:2 row_mask:0xf bank_mask:0xf
	v_fmac_f32_dpp v165, v45, v105 row_shr:2 row_mask:0xf bank_mask:0xf
	v_fmac_f32_dpp v166, v46, v106 row_shr:2 row_mask:0xf bank_mask:0xf
	v_fmac_f32_dpp v167, v47, v107 row_shr:2 row_mask:0xf bank_mask:0xf
	v_mul_f32_e32 v168, 0xbfb8aa3b, v160
	v_mul_f32_e32 v169, 0xbfb8aa3b, v161
	v_mul_f32_e32 v170, 0xbfb8aa3b, v162
	v_mul_f32_e32 v171, 0xbfb8aa3b, v163
	v_exp_f32_e32 v168, v168
	v_exp_f32_e32 v169, v169
	v_exp_f32_e32 v170, v170
	v_exp_f32_e32 v171, v171
	v_add_f32_e32 v168, 1.0, v168
	v_add_f32_e32 v169, 1.0, v169
	v_add_f32_e32 v170, 1.0, v170
	v_add_f32_e32 v171, 1.0, v171
	v_rcp_f32_e32 v168, v168
	v_rcp_f32_e32 v169, v169
	v_rcp_f32_e32 v170, v170
	v_rcp_f32_e32 v171, v171
	v_mov_b64_e32 v[174:175], v[224:225]
	v_mul_f32_e32 v160, v160, v168
	v_mul_f32_e32 v161, v161, v169
	v_mul_f32_e32 v162, v162, v170
	v_mul_f32_e32 v163, v163, v171
	v_mul_f32_e32 v160, v164, v160
	v_mul_f32_e32 v161, v165, v161
	v_mul_f32_e32 v162, v166, v162
	v_mul_f32_e32 v163, v167, v163
	v_cvt_pk_bf16_f32 v172, v160, v161
	v_cvt_pk_bf16_f32 v173, v162, v163
	s_and_saveexec_b64 s[76:77], s[38:39]
	global_store_dwordx2 v[174:175], v[172:173], off
	s_or_b64 exec, exec, s[76:77]
	s_ashr_i32 s80, s71, 6
	s_lshl_b32 s80, s80, 2
	s_add_i32 s80, s80, 8
	v_add_u32_e32 v226, s80, v188
	v_mov_b64_e32 v[174:175], s[8:9]
	s_movk_i32 s80, 0x5800
	v_mad_i64_i32 v[174:175], s[78:79], v226, s80, v[174:175]
	v_lshl_add_u64 v[174:175], v[228:229], 2, v[174:175]
	s_and_saveexec_b64 s[76:77], s[40:41]
	global_store_dwordx4 v[174:175], v[48:51], off
	global_store_dwordx4 v[174:175], v[44:47], off offset:16
	s_or_b64 exec, exec, s[76:77]
	v_fma_f32 v208, v100, v24, v124
	v_fma_f32 v209, v101, v25, v125
	v_fma_f32 v210, v102, v26, v126
	v_fma_f32 v211, v103, v27, v127
	v_fma_f32 v212, v120, v20, v72
	v_fma_f32 v213, v121, v21, v73
	v_fma_f32 v214, v122, v22, v74
	v_fma_f32 v215, v123, v23, v75
	v_fmac_f32_dpp v208, v24, v88 row_shr:1 row_mask:0xf bank_mask:0xf
	v_fmac_f32_dpp v209, v25, v89 row_shr:1 row_mask:0xf bank_mask:0xf
; DI float silu_fast(float x) { return x * __builtin_amdgcn_rcpf(1.f + __expf(-x)); }
; template <int CTRL> DI float dppf(float v) { return __builtin_bit_cast(float, __builtin_amdgcn_update_dpp(0, __builtin_bit_cast(int, v), CTRL, 0xf, 0xf, true)); }
; DI void Epi::fused(const f32x4 (&acc)[2][2][4][2], int pm, int pn, int wr, int wc, int fr, int fq) const {
;     ...
;             for (int m = 0; m < 4; ++m) {
;                 const f32x4 ca = acc[ai][bj][m][0], cb = acc[ai][bj][m][1];
;                 const int row = pm * 256 + ai * 128 + wr * 64 + m * 16 + fr;
;                 float o[4];
; #pragma unroll
;                 for (int e = 0; e < 4; ++e) {
;                     const float a1 = dppf<0x111>(ca[e]) + dppf<0x10F>(pa[e]), a2 = dppf<0x112>(ca[e]) + dppf<0x10E>(pa[e]);
;                     const float b1 = dppf<0x111>(cb[e]) + dppf<0x10F>(pb[e]), b2 = dppf<0x112>(cb[e]) + dppf<0x10E>(pb[e]);
;                     const float ya = fmaf(wa0[e], a2, fmaf(wa1[e], a1, fmaf(wa2[e], ca[e], ba[e])));
;                     const float yb = fmaf(wb0[e], b2, fmaf(wb1[e], b1, fmaf(wb2[e], cb[e], bb[e])));
;                     o[e] = silu_fast(ya) * yb; }
;                 if (m > 0 || fr >= 2) { u32x2 w; w.x = pk2(o[0], o[1]); w.y = pk2(o[2], o[3]); *(u32x2*)(E.d0 + (size_t)row * FFH + j0) = w; }
;                 if ((m == 0 && fr < 2) || (m == 3 && fr >= 14)) { float* hb = E.f0 + ((size_t)(row >> 6) * 4 + (m == 0 ? fr : fr - 12)) * FF2 + ncol; *(f32x4*)hb = ca; *(f32x4*)(hb + 4) = cb; }
;                 pa = ca; pb = cb;
	v_fmac_f32_dpp v210, v26, v90 row_shr:1 row_mask:0xf bank_mask:0xf
	v_fmac_f32_dpp v211, v27, v91 row_shr:1 row_mask:0xf bank_mask:0xf
	v_fmac_f32_dpp v212, v20, v116 row_shr:1 row_mask:0xf bank_mask:0xf
	v_fmac_f32_dpp v213, v21, v117 row_shr:1 row_mask:0xf bank_mask:0xf
	v_fmac_f32_dpp v214, v22, v118 row_shr:1 row_mask:0xf bank_mask:0xf
	v_fmac_f32_dpp v215, v23, v119 row_shr:1 row_mask:0xf bank_mask:0xf
	v_fmac_f32_dpp v208, v48, v88 row_shl:15 row_mask:0xf bank_mask:0xf
	v_fmac_f32_dpp v209, v49, v89 row_shl:15 row_mask:0xf bank_mask:0xf
	v_fmac_f32_dpp v210, v50, v90 row_shl:15 row_mask:0xf bank_mask:0xf
	v_fmac_f32_dpp v211, v51, v91 row_shl:15 row_mask:0xf bank_mask:0xf
	v_fmac_f32_dpp v212, v44, v116 row_shl:15 row_mask:0xf bank_mask:0xf
	v_fmac_f32_dpp v213, v45, v117 row_shl:15 row_mask:0xf bank_mask:0xf
	v_fmac_f32_dpp v214, v46, v118 row_shl:15 row_mask:0xf bank_mask:0xf
	v_fmac_f32_dpp v215, v47, v119 row_shl:15 row_mask:0xf bank_mask:0xf
	v_fmac_f32_dpp v208, v24, v84 row_shr:2 row_mask:0xf bank_mask:0xf
	v_fmac_f32_dpp v209, v25, v85 row_shr:2 row_mask:0xf bank_mask:0xf
	v_fmac_f32_dpp v210, v26, v86 row_shr:2 row_mask:0xf bank_mask:0xf
	v_fmac_f32_dpp v211, v27, v87 row_shr:2 row_mask:0xf bank_mask:0xf
	v_fmac_f32_dpp v212, v20, v104 row_shr:2 row_mask:0xf bank_mask:0xf
	v_fmac_f32_dpp v213, v21, v105 row_shr:2 row_mask:0xf bank_mask:0xf
	v_fmac_f32_dpp v214, v22, v106 row_shr:2 row_mask:0xf bank_mask:0xf
	v_fmac_f32_dpp v215, v23, v107 row_shr:2 row_mask:0xf bank_mask:0xf
	v_fmac_f32_dpp v208, v48, v84 row_shl:14 row_mask:0xf bank_mask:0xf
	v_fmac_f32_dpp v209, v49, v85 row_shl:14 row_mask:0xf bank_mask:0xf
	v_fmac_f32_dpp v210, v50, v86 row_shl:14 row_mask:0xf bank_mask:0xf
	v_fmac_f32_dpp v211, v51, v87 row_shl:14 row_mask:0xf bank_mask:0xf
	v_fmac_f32_dpp v212, v44, v104 row_shl:14 row_mask:0xf bank_mask:0xf
	v_fmac_f32_dpp v213, v45, v105 row_shl:14 row_mask:0xf bank_mask:0xf
	v_fmac_f32_dpp v214, v46, v106 row_shl:14 row_mask:0xf bank_mask:0xf
	v_fmac_f32_dpp v215, v47, v107 row_shl:14 row_mask:0xf bank_mask:0xf
	v_mul_f32_e32 v216, 0xbfb8aa3b, v208
	v_mul_f32_e32 v217, 0xbfb8aa3b, v209
	v_mul_f32_e32 v218, 0xbfb8aa3b, v210
	v_mul_f32_e32 v219, 0xbfb8aa3b, v211
	v_exp_f32_e32 v216, v216
	v_exp_f32_e32 v217, v217
	v_exp_f32_e32 v218, v218
	v_exp_f32_e32 v219, v219
	v_add_f32_e32 v216, 1.0, v216
	v_add_f32_e32 v217, 1.0, v217
	v_add_f32_e32 v218, 1.0, v218
	v_add_f32_e32 v219, 1.0, v219
	v_rcp_f32_e32 v216, v216
	v_rcp_f32_e32 v217, v217
	v_rcp_f32_e32 v218, v218
	v_rcp_f32_e32 v219, v219
	s_mov_b32 s80, 0x16000
	s_mov_b32 s81, 0
	v_lshl_add_u64 v[222:223], v[224:225], 0, s[80:81]
	v_mul_f32_e32 v208, v208, v216
	v_mul_f32_e32 v209, v209, v217
	v_mul_f32_e32 v210, v210, v218
	v_mul_f32_e32 v211, v211, v219
	v_mul_f32_e32 v208, v212, v208
	v_mul_f32_e32 v209, v213, v209
	v_mul_f32_e32 v210, v214, v210
	v_mul_f32_e32 v211, v215, v211
	v_cvt_pk_bf16_f32 v220, v208, v209
	v_cvt_pk_bf16_f32 v221, v210, v211
	global_store_dwordx2 v[222:223], v[220:221], off
	v_fma_f32 v160, v100, v28, v124
	v_fma_f32 v161, v101, v29, v125
	v_fma_f32 v162, v102, v30, v126
	v_fma_f32 v163, v103, v31, v127
	v_fma_f32 v164, v120, v32, v72
	v_fma_f32 v165, v121, v33, v73
	v_fma_f32 v166, v122, v34, v74
	v_fma_f32 v167, v123, v35, v75
	v_fmac_f32_dpp v160, v28, v88 row_shr:1 row_mask:0xf bank_mask:0xf
	v_fmac_f32_dpp v161, v29, v89 row_shr:1 row_mask:0xf bank_mask:0xf
	v_fmac_f32_dpp v162, v30, v90 row_shr:1 row_mask:0xf bank_mask:0xf
	v_fmac_f32_dpp v163, v31, v91 row_shr:1 row_mask:0xf bank_mask:0xf
	v_fmac_f32_dpp v164, v32, v116 row_shr:1 row_mask:0xf bank_mask:0xf
	v_fmac_f32_dpp v165, v33, v117 row_shr:1 row_mask:0xf bank_mask:0xf
	v_fmac_f32_dpp v166, v34, v118 row_shr:1 row_mask:0xf bank_mask:0xf
	v_fmac_f32_dpp v167, v35, v119 row_shr:1 row_mask:0xf bank_mask:0xf
	v_fmac_f32_dpp v160, v24, v88 row_shl:15 row_mask:0xf bank_mask:0xf
	v_fmac_f32_dpp v161, v25, v89 row_shl:15 row_mask:0xf bank_mask:0xf
	v_fmac_f32_dpp v162, v26, v90 row_shl:15 row_mask:0xf bank_mask:0xf
	v_fmac_f32_dpp v163, v27, v91 row_shl:15 row_mask:0xf bank_mask:0xf
	v_fmac_f32_dpp v164, v20, v116 row_shl:15 row_mask:0xf bank_mask:0xf
	v_fmac_f32_dpp v165, v21, v117 row_shl:15 row_mask:0xf bank_mask:0xf
	v_fmac_f32_dpp v166, v22, v118 row_shl:15 row_mask:0xf bank_mask:0xf
	v_fmac_f32_dpp v167, v23, v119 row_shl:15 row_mask:0xf bank_mask:0xf
	v_fmac_f32_dpp v160, v28, v84 row_shr:2 row_mask:0xf bank_mask:0xf
	v_fmac_f32_dpp v161, v29, v85 row_shr:2 row_mask:0xf bank_mask:0xf
	v_fmac_f32_dpp v162, v30, v86 row_shr:2 row_mask:0xf bank_mask:0xf
	v_fmac_f32_dpp v163, v31, v87 row_shr:2 row_mask:0xf bank_mask:0xf
	v_fmac_f32_dpp v164, v32, v104 row_shr:2 row_mask:0xf bank_mask:0xf
	v_fmac_f32_dpp v165, v33, v105 row_shr:2 row_mask:0xf bank_mask:0xf
	v_fmac_f32_dpp v166, v34, v106 row_shr:2 row_mask:0xf bank_mask:0xf
	v_fmac_f32_dpp v167, v35, v107 row_shr:2 row_mask:0xf bank_mask:0xf
	v_fmac_f32_dpp v160, v24, v84 row_shl:14 row_mask:0xf bank_mask:0xf
	v_fmac_f32_dpp v161, v25, v85 row_shl:14 row_mask:0xf bank_mask:0xf
	v_fmac_f32_dpp v162, v26, v86 row_shl:14 row_mask:0xf bank_mask:0xf
; DI float silu_fast(float x) { return x * __builtin_amdgcn_rcpf(1.f + __expf(-x)); }
; template <int CTRL> DI float dppf(float v) { return __builtin_bit_cast(float, __builtin_amdgcn_update_dpp(0, __builtin_bit_cast(int, v), CTRL, 0xf, 0xf, true)); }
; DI void Epi::fused(const f32x4 (&acc)[2][2][4][2], int pm, int pn, int wr, int wc, int fr, int fq) const {
;     ...
;             for (int m = 0; m < 4; ++m) {
;                 const f32x4 ca = acc[ai][bj][m][0], cb = acc[ai][bj][m][1];
;                 const int row = pm * 256 + ai * 128 + wr * 64 + m * 16 + fr;
;                 float o[4];
; #pragma unroll
;                 for (int e = 0; e < 4; ++e) {
;                     const float a1 = dppf<0x111>(ca[e]) + dppf<0x10F>(pa[e]), a2 = dppf<0x112>(ca[e]) + dppf<0x10E>(pa[e]);
;                     const float b1 = dppf<0x111>(cb[e]) + dppf<0x10F>(pb[e]), b2 = dppf<0x112>(cb[e]) + dppf<0x10E>(pb[e]);
;                     const float ya = fmaf(wa0[e], a2, fmaf(wa1[e], a1, fmaf(wa2[e], ca[e], ba[e])));
;                     const float yb = fmaf(wb0[e], b2, fmaf(wb1[e], b1, fmaf(wb2[e], cb[e], bb[e])));
;                     o[e] = silu_fast(ya) * yb; }
;                 if (m > 0 || fr >= 2) { u32x2 w; w.x = pk2(o[0], o[1]); w.y = pk2(o[2], o[3]); *(u32x2*)(E.d0 + (size_t)row * FFH + j0) = w; }
;                 if ((m == 0 && fr < 2) || (m == 3 && fr >= 14)) { float* hb = E.f0 + ((size_t)(row >> 6) * 4 + (m == 0 ? fr : fr - 12)) * FF2 + ncol; *(f32x4*)hb = ca; *(f32x4*)(hb + 4) = cb; }
;                 pa = ca; pb = cb;
	v_fmac_f32_dpp v163, v27, v87 row_shl:14 row_mask:0xf bank_mask:0xf
	v_fmac_f32_dpp v164, v20, v104 row_shl:14 row_mask:0xf bank_mask:0xf
	v_fmac_f32_dpp v165, v21, v105 row_shl:14 row_mask:0xf bank_mask:0xf
	v_fmac_f32_dpp v166, v22, v106 row_shl:14 row_mask:0xf bank_mask:0xf
	v_fmac_f32_dpp v167, v23, v107 row_shl:14 row_mask:0xf bank_mask:0xf
	v_mul_f32_e32 v168, 0xbfb8aa3b, v160
	v_mul_f32_e32 v169, 0xbfb8aa3b, v161
	v_mul_f32_e32 v170, 0xbfb8aa3b, v162
	v_mul_f32_e32 v171, 0xbfb8aa3b, v163
	v_exp_f32_e32 v168, v168
	v_exp_f32_e32 v169, v169
	v_exp_f32_e32 v170, v170
	v_exp_f32_e32 v171, v171
	v_add_f32_e32 v168, 1.0, v168
	v_add_f32_e32 v169, 1.0, v169
	v_add_f32_e32 v170, 1.0, v170
	v_add_f32_e32 v171, 1.0, v171
	v_rcp_f32_e32 v168, v168
	v_rcp_f32_e32 v169, v169
	v_rcp_f32_e32 v170, v170
	v_rcp_f32_e32 v171, v171
	s_mov_b32 s80, 0x2c000
	s_mov_b32 s81, 0
	v_lshl_add_u64 v[174:175], v[224:225], 0, s[80:81]
	v_mul_f32_e32 v160, v160, v168
	v_mul_f32_e32 v161, v161, v169
	v_mul_f32_e32 v162, v162, v170
	v_mul_f32_e32 v163, v163, v171
	v_mul_f32_e32 v160, v164, v160
	v_mul_f32_e32 v161, v165, v161
	v_mul_f32_e32 v162, v166, v162
	v_mul_f32_e32 v163, v167, v163
	v_cvt_pk_bf16_f32 v172, v160, v161
	v_cvt_pk_bf16_f32 v173, v162, v163
	global_store_dwordx2 v[174:175], v[172:173], off
	v_fma_f32 v208, v100, v8, v124
	v_fma_f32 v209, v101, v9, v125
	v_fma_f32 v210, v102, v10, v126
	v_fma_f32 v211, v103, v11, v127
	v_fma_f32 v212, v120, v4, v72
	v_fma_f32 v213, v121, v5, v73
	v_fma_f32 v214, v122, v6, v74
	v_fma_f32 v215, v123, v7, v75
	v_fmac_f32_dpp v208, v8, v88 row_shr:1 row_mask:0xf bank_mask:0xf
	v_fmac_f32_dpp v209, v9, v89 row_shr:1 row_mask:0xf bank_mask:0xf
	v_fmac_f32_dpp v210, v10, v90 row_shr:1 row_mask:0xf bank_mask:0xf
	v_fmac_f32_dpp v211, v11, v91 row_shr:1 row_mask:0xf bank_mask:0xf
	v_fmac_f32_dpp v212, v4, v116 row_shr:1 row_mask:0xf bank_mask:0xf
	v_fmac_f32_dpp v213, v5, v117 row_shr:1 row_mask:0xf bank_mask:0xf
	v_fmac_f32_dpp v214, v6, v118 row_shr:1 row_mask:0xf bank_mask:0xf
	v_fmac_f32_dpp v215, v7, v119 row_shr:1 row_mask:0xf bank_mask:0xf
	v_fmac_f32_dpp v208, v28, v88 row_shl:15 row_mask:0xf bank_mask:0xf
	v_fmac_f32_dpp v209, v29, v89 row_shl:15 row_mask:0xf bank_mask:0xf
	v_fmac_f32_dpp v210, v30, v90 row_shl:15 row_mask:0xf bank_mask:0xf
	v_fmac_f32_dpp v211, v31, v91 row_shl:15 row_mask:0xf bank_mask:0xf
	v_fmac_f32_dpp v212, v32, v116 row_shl:15 row_mask:0xf bank_mask:0xf
	v_fmac_f32_dpp v213, v33, v117 row_shl:15 row_mask:0xf bank_mask:0xf
	v_fmac_f32_dpp v214, v34, v118 row_shl:15 row_mask:0xf bank_mask:0xf
	v_fmac_f32_dpp v215, v35, v119 row_shl:15 row_mask:0xf bank_mask:0xf
	v_fmac_f32_dpp v208, v8, v84 row_shr:2 row_mask:0xf bank_mask:0xf
	v_fmac_f32_dpp v209, v9, v85 row_shr:2 row_mask:0xf bank_mask:0xf
	v_fmac_f32_dpp v210, v10, v86 row_shr:2 row_mask:0xf bank_mask:0xf
	v_fmac_f32_dpp v211, v11, v87 row_shr:2 row_mask:0xf bank_mask:0xf
	v_fmac_f32_dpp v212, v4, v104 row_shr:2 row_mask:0xf bank_mask:0xf
	v_fmac_f32_dpp v213, v5, v105 row_shr:2 row_mask:0xf bank_mask:0xf
	v_fmac_f32_dpp v214, v6, v106 row_shr:2 row_mask:0xf bank_mask:0xf
	v_fmac_f32_dpp v215, v7, v107 row_shr:2 row_mask:0xf bank_mask:0xf
	v_fmac_f32_dpp v208, v28, v84 row_shl:14 row_mask:0xf bank_mask:0xf
	v_fmac_f32_dpp v209, v29, v85 row_shl:14 row_mask:0xf bank_mask:0xf
	v_fmac_f32_dpp v210, v30, v86 row_shl:14 row_mask:0xf bank_mask:0xf
	v_fmac_f32_dpp v211, v31, v87 row_shl:14 row_mask:0xf bank_mask:0xf
	v_fmac_f32_dpp v212, v32, v104 row_shl:14 row_mask:0xf bank_mask:0xf
	v_fmac_f32_dpp v213, v33, v105 row_shl:14 row_mask:0xf bank_mask:0xf
	v_fmac_f32_dpp v214, v34, v106 row_shl:14 row_mask:0xf bank_mask:0xf
	v_fmac_f32_dpp v215, v35, v107 row_shl:14 row_mask:0xf bank_mask:0xf
	v_mul_f32_e32 v216, 0xbfb8aa3b, v208
	v_mul_f32_e32 v217, 0xbfb8aa3b, v209
	v_mul_f32_e32 v218, 0xbfb8aa3b, v210
	v_mul_f32_e32 v219, 0xbfb8aa3b, v211
	v_exp_f32_e32 v216, v216
	v_exp_f32_e32 v217, v217
	v_exp_f32_e32 v218, v218
	v_exp_f32_e32 v219, v219
	v_add_f32_e32 v216, 1.0, v216
	v_add_f32_e32 v217, 1.0, v217
	v_add_f32_e32 v218, 1.0, v218
	v_add_f32_e32 v219, 1.0, v219
	v_rcp_f32_e32 v216, v216
	v_rcp_f32_e32 v217, v217
	v_rcp_f32_e32 v218, v218
	v_rcp_f32_e32 v219, v219
	s_mov_b32 s80, 0x42000
	s_mov_b32 s81, 0
	v_lshl_add_u64 v[222:223], v[224:225], 0, s[80:81]
	v_mul_f32_e32 v208, v208, v216
	v_mul_f32_e32 v209, v209, v217
	v_mul_f32_e32 v210, v210, v218
	v_mul_f32_e32 v211, v211, v219
	v_mul_f32_e32 v208, v212, v208
	v_mul_f32_e32 v209, v213, v209
	v_mul_f32_e32 v210, v214, v210
	v_mul_f32_e32 v211, v215, v211
	v_cvt_pk_bf16_f32 v220, v208, v209
	v_cvt_pk_bf16_f32 v221, v210, v211
	global_store_dwordx2 v[222:223], v[220:221], off
	s_ashr_i32 s80, s71, 6
	s_lshl_b32 s80, s80, 2
	s_add_i32 s80, s80, 8
	v_add_u32_e32 v226, s80, v190
	v_mov_b64_e32 v[222:223], s[8:9]
	s_movk_i32 s80, 0x5800
	v_mad_i64_i32 v[222:223], s[78:79], v226, s80, v[222:223]
	v_lshl_add_u64 v[222:223], v[228:229], 2, v[222:223]
	s_and_saveexec_b64 s[76:77], s[42:43]
	global_store_dwordx4 v[222:223], v[8:11], off
	global_store_dwordx4 v[222:223], v[4:7], off offset:16
	s_or_b64 exec, exec, s[76:77]

; DI void xcd_barrier(const XcdBarrier& b) {
;     asm volatile("s_waitcnt vmcnt(0)" ::: "memory");
;     __syncthreads();
;     if (threadIdx.x == 0) {
;         unsigned* bar = b.bar;
;         __builtin_amdgcn_s_waitcnt(0);
;         unsigned nloc = b.st[0], nx = b.st[1];
;         if (nloc == 0u) { xcd_barrier_complete(bar, b.x, nloc, nx); b.st[0] = nloc; b.st[1] = nx; }
.LBB0_1660:
	s_waitcnt vmcnt(0)
	s_setprio 0
	s_waitcnt vmcnt(0) lgkmcnt(0)
	s_barrier
	s_mov_b64 s[0:1], exec
	v_readlane_b32 s4, v251, 46
	v_readlane_b32 s5, v251, 47
	s_and_b64 s[4:5], s[0:1], s[4:5]
	s_mov_b64 exec, s[4:5]
	s_cbranch_execnz .LBB0_1661
	s_getpc_b64 s[98:99]
